# speedup vs baseline: 1.0433x; 1.0021x over previous
; #define PG8_STAGE(bufoff, gbase, voff) do { _Pragma("unroll") for (int _i = 0; _i < 2; ++_i) \
;         __builtin_amdgcn_global_load_lds((const unsigned*)((const char*)(gbase) + (voff)[_i]), (LAS unsigned*)(lds + (bufoff) + ldsw + _i * 8192), 16, 0, 0); } while (0)
; #define PG8_LDA(dst, b, h) do { _Pragma("unroll") for (int m = 0; m < 4; ++m) _Pragma("unroll") for (int k = 0; k < 2; ++k) dst[m][k] = *(const LAS bf16x8*)(lds + PG8_SA(b, h) + aoff + m * 2048 + k * 1024); } while (0)
; #define PG8_LDB(dst, b, h) do { _Pragma("unroll") for (int n = 0; n < 2; ++n) _Pragma("unroll") for (int k = 0; k < 2; ++k) dst[n][k] = *(const LAS bf16x8*)(lds + PG8_SB(b, h) + boff + n * 2048 + k * 1024); } while (0)
; #define PG8_WAIT_V(n) asm volatile("s_waitcnt vmcnt(" #n ")" ::: "memory")
; #define PG8_WAIT_L(n) asm volatile("s_waitcnt lgkmcnt(" #n ")" ::: "memory")
; #define PG8_BAR __builtin_amdgcn_s_barrier()
; #define PG8_SCHED __builtin_amdgcn_sched_barrier(0)
; template <class Epi, class Sched, bool FUSED = false, bool APERM = false>
; __device__ __forceinline__ void gemm_phase(int wid_s, LAS unsigned char* lds, const Gemm g, const Sched& S, const Epi& E) {
;     ...
;             const bool last = (t == nt - 2);
;             const char* a1 = cA + (size_t)(t + 1) * kstep;
;             const char* a2 = last ? nA : cA + (size_t)(t + 2) * kstep; const char* b2 = last ? nB : cB + (size_t)(t + 2) * kstep;
;             const char* a3 = a2 + kstep; const char* b3 = b2 + kstep;
;             if (last && has_next) S.a_ready(nxt);
;             PG8_LDB(B0, 0, 0); PG8_LDB(B1, 0, 1); PG8_SCHED; PG8_LDA(At, 0, 0); PG8_STAGE(PG8_SA(1, 1), a1 + hstep, voffA);
;             PG8_WAIT_V(8); PG8_WAIT_L(0); PG8_BAR; PG8_MMA(0, 0, At, B0); PG8_MMA(0, 1, At, B1); PG8_BAR; PG8_SCHED;
;             PG8_LDA(At, 0, 1); PG8_STAGE(PG8_SB(0, 0), b2, voffB); PG8_STAGE(PG8_SB(0, 1), b2 + hstep, voffB); PG8_STAGE(PG8_SA(0, 0), a2, voffA);
.LBB0_145:
	s_add_u32 s42, s40, 0xfff80080
	s_addc_u32 s43, s41, -1
	s_add_i32 s68, 0, 0x10000
	s_cmp_eq_u32 s67, 28
	s_cselect_b32 s45, s3, s43
	s_cselect_b32 s44, s10, s42
	s_cselect_b32 s43, s25, s66
	s_cselect_b32 s42, s27, s35
	s_add_i32 s70, 0, 0x14000
	v_add_u32_e32 v144, s68, v227
	v_add_u32_e32 v160, s70, v227
	ds_read_b128 v[132:135], v144
	ds_read_b128 v[136:139], v144 offset:1024
	ds_read_b128 v[140:143], v144 offset:2048
	ds_read_b128 v[144:147], v144 offset:3072
	ds_read_b128 v[148:151], v160
	ds_read_b128 v[152:155], v160 offset:1024
	ds_read_b128 v[156:159], v160 offset:2048
	ds_read_b128 v[160:163], v160 offset:3072
	v_lshl_add_u64 v[214:215], s[40:41], 0, v[212:213]
	s_add_i32 m0, s52, 0xc000
	ds_read_b128 v[164:167], v228
	ds_read_b128 v[168:171], v228 offset:1024
	ds_read_b128 v[172:175], v228 offset:2048
	ds_read_b128 v[176:179], v228 offset:3072
	ds_read_b128 v[180:183], v228 offset:4096
	ds_read_b128 v[184:187], v228 offset:5120
	ds_read_b128 v[188:191], v228 offset:6144
	ds_read_b128 v[192:195], v228 offset:7168
	global_load_lds_dwordx4 v[214:215], off
	v_lshl_add_u64 v[214:215], s[40:41], 0, v[210:211]
	s_add_i32 m0, s52, 0xe000
	s_nop 0
	global_load_lds_dwordx4 v[214:215], off
	s_waitcnt vmcnt(8)
	s_waitcnt lgkmcnt(0)
	s_barrier
	s_waitcnt lgkmcnt(0)
	v_mfma_f32_16x16x32_f16 v[128:131], v[132:135], v[164:167], v[128:131]
	v_mfma_f32_16x16x32_f16 v[124:127], v[140:143], v[164:167], v[124:127]
	v_mfma_f32_16x16x32_f16 v[112:115], v[132:135], v[172:175], v[112:115]
	v_mfma_f32_16x16x32_f16 v[108:111], v[140:143], v[172:175], v[108:111]
	v_mfma_f32_16x16x32_f16 v[96:99], v[132:135], v[180:183], v[96:99]
	v_mfma_f32_16x16x32_f16 v[92:95], v[140:143], v[180:183], v[92:95]
	v_mfma_f32_16x16x32_f16 v[80:83], v[132:135], v[188:191], v[80:83]
	v_mfma_f32_16x16x32_f16 v[76:79], v[140:143], v[188:191], v[76:79]
	v_mfma_f32_16x16x32_f16 v[128:131], v[136:139], v[168:171], v[128:131]
	v_mfma_f32_16x16x32_f16 v[124:127], v[144:147], v[168:171], v[124:127]
	v_mfma_f32_16x16x32_f16 v[112:115], v[136:139], v[176:179], v[112:115]
	v_mfma_f32_16x16x32_f16 v[108:111], v[144:147], v[176:179], v[108:111]
	v_mfma_f32_16x16x32_f16 v[96:99], v[136:139], v[184:187], v[96:99]
	v_mfma_f32_16x16x32_f16 v[92:95], v[144:147], v[184:187], v[92:95]
	v_mfma_f32_16x16x32_f16 v[80:83], v[136:139], v[192:195], v[80:83]
	v_mfma_f32_16x16x32_f16 v[76:79], v[144:147], v[192:195], v[76:79]
	v_mfma_f32_16x16x32_f16 v[120:123], v[148:151], v[164:167], v[120:123]
	v_mfma_f32_16x16x32_f16 v[116:119], v[156:159], v[164:167], v[116:119]
	v_mfma_f32_16x16x32_f16 v[104:107], v[148:151], v[172:175], v[104:107]
	v_mfma_f32_16x16x32_f16 v[100:103], v[156:159], v[172:175], v[100:103]
	v_mfma_f32_16x16x32_f16 v[88:91], v[148:151], v[180:183], v[88:91]
	v_mfma_f32_16x16x32_f16 v[84:87], v[156:159], v[180:183], v[84:87]
	v_mfma_f32_16x16x32_f16 v[68:71], v[148:151], v[188:191], v[68:71]
	v_mfma_f32_16x16x32_f16 v[72:75], v[156:159], v[188:191], v[72:75]
	v_mfma_f32_16x16x32_f16 v[120:123], v[152:155], v[168:171], v[120:123]
	v_mfma_f32_16x16x32_f16 v[116:119], v[160:163], v[168:171], v[116:119]
	v_mfma_f32_16x16x32_f16 v[104:107], v[152:155], v[176:179], v[104:107]
	v_mfma_f32_16x16x32_f16 v[100:103], v[160:163], v[176:179], v[100:103]
	v_mfma_f32_16x16x32_f16 v[88:91], v[152:155], v[184:187], v[88:91]
	v_mfma_f32_16x16x32_f16 v[84:87], v[160:163], v[184:187], v[84:87]
	v_mfma_f32_16x16x32_f16 v[68:71], v[152:155], v[192:195], v[68:71]
	v_mfma_f32_16x16x32_f16 v[72:75], v[160:163], v[192:195], v[72:75]
	s_barrier
	s_add_i32 s68, s68, s51
	v_lshl_add_u64 v[214:215], s[42:43], 0, v[0:1]
	s_mov_b32 m0, s68
	ds_read_b128 v[164:167], v228 offset:16384
	ds_read_b128 v[168:171], v228 offset:17408
	ds_read_b128 v[172:175], v228 offset:18432
	ds_read_b128 v[176:179], v228 offset:19456
	ds_read_b128 v[180:183], v228 offset:20480
	ds_read_b128 v[184:187], v228 offset:21504
	ds_read_b128 v[188:191], v228 offset:22528
	ds_read_b128 v[192:195], v228 offset:23552
	global_load_lds_dwordx4 v[214:215], off
	s_add_i32 m0, s68, 0x2000
	s_add_u32 s68, s42, 0x80000
	v_lshl_add_u64 v[216:217], s[42:43], 0, v[208:209]
	s_addc_u32 s69, s43, 0
	s_add_i32 s70, s70, s51
	global_load_lds_dwordx4 v[216:217], off
	v_lshl_add_u64 v[218:219], s[68:69], 0, v[0:1]
	s_mov_b32 m0, s70
	v_lshl_add_u64 v[220:221], s[44:45], 0, v[208:209]
	global_load_lds_dwordx4 v[218:219], off
	v_lshl_add_u64 v[218:219], s[68:69], 0, v[208:209]
	s_add_i32 m0, s70, 0x2000
	s_nop 0
	global_load_lds_dwordx4 v[218:219], off
	v_lshl_add_u64 v[218:219], s[44:45], 0, v[0:1]
	s_mov_b32 m0, s52
	s_nop 0
	global_load_lds_dwordx4 v[218:219], off
	s_mov_b32 m0, s53
	s_nop 0
	global_load_lds_dwordx4 v[220:221], off
	s_waitcnt vmcnt(8)
	s_waitcnt lgkmcnt(0)
	s_barrier
; #define PG8_STAGE(bufoff, gbase, voff) do { _Pragma("unroll") for (int _i = 0; _i < 2; ++_i) \
;         __builtin_amdgcn_global_load_lds((const unsigned*)((const char*)(gbase) + (voff)[_i]), (LAS unsigned*)(lds + (bufoff) + ldsw + _i * 8192), 16, 0, 0); } while (0)
; #define PG8_LDA(dst, b, h) do { _Pragma("unroll") for (int m = 0; m < 4; ++m) _Pragma("unroll") for (int k = 0; k < 2; ++k) dst[m][k] = *(const LAS bf16x8*)(lds + PG8_SA(b, h) + aoff + m * 2048 + k * 1024); } while (0)
; #define PG8_LDB(dst, b, h) do { _Pragma("unroll") for (int n = 0; n < 2; ++n) _Pragma("unroll") for (int k = 0; k < 2; ++k) dst[n][k] = *(const LAS bf16x8*)(lds + PG8_SB(b, h) + boff + n * 2048 + k * 1024); } while (0)
; #define PG8_WAIT_V(n) asm volatile("s_waitcnt vmcnt(" #n ")" ::: "memory")
; #define PG8_WAIT_L(n) asm volatile("s_waitcnt lgkmcnt(" #n ")" ::: "memory")
; #define PG8_BAR __builtin_amdgcn_s_barrier()
; #define PG8_SCHED __builtin_amdgcn_sched_barrier(0)
; template <class Epi, class Sched, bool FUSED = false, bool APERM = false>
; __device__ __forceinline__ void gemm_phase(int wid_s, LAS unsigned char* lds, const Gemm g, const Sched& S, const Epi& E) {
;     ...
;             PG8_WAIT_V(8); PG8_WAIT_L(0); PG8_BAR; PG8_MMA(1, 0, At, B0); PG8_MMA(1, 1, At, B1); PG8_BAR; PG8_SCHED;
;             PG8_LDB(B0, 1, 0); PG8_LDB(B1, 1, 1); PG8_SCHED; PG8_LDA(At, 1, 0); PG8_STAGE(PG8_SA(0, 1), a2 + hstep, voffA);
;             PG8_WAIT_V(8); PG8_WAIT_L(0); PG8_BAR; PG8_MMA(0, 0, At, B0); PG8_MMA(0, 1, At, B1); PG8_BAR; PG8_SCHED;
	s_waitcnt lgkmcnt(0)
	v_mfma_f32_16x16x32_f16 v[64:67], v[132:135], v[164:167], v[64:67]
	v_mfma_f32_16x16x32_f16 v[60:63], v[140:143], v[164:167], v[60:63]
	v_mfma_f32_16x16x32_f16 v[48:51], v[132:135], v[172:175], v[48:51]
	v_mfma_f32_16x16x32_f16 v[44:47], v[140:143], v[172:175], v[44:47]
	v_mfma_f32_16x16x32_f16 v[32:35], v[132:135], v[180:183], v[32:35]
	v_mfma_f32_16x16x32_f16 v[28:31], v[140:143], v[180:183], v[28:31]
	v_mfma_f32_16x16x32_f16 v[12:15], v[132:135], v[188:191], v[12:15]
	v_mfma_f32_16x16x32_f16 v[16:19], v[140:143], v[188:191], v[16:19]
	v_mfma_f32_16x16x32_f16 v[64:67], v[136:139], v[168:171], v[64:67]
	v_mfma_f32_16x16x32_f16 v[60:63], v[144:147], v[168:171], v[60:63]
	v_mfma_f32_16x16x32_f16 v[48:51], v[136:139], v[176:179], v[48:51]
	v_mfma_f32_16x16x32_f16 v[44:47], v[144:147], v[176:179], v[44:47]
	v_mfma_f32_16x16x32_f16 v[32:35], v[136:139], v[184:187], v[32:35]
	v_mfma_f32_16x16x32_f16 v[28:31], v[144:147], v[184:187], v[28:31]
	v_mfma_f32_16x16x32_f16 v[12:15], v[136:139], v[192:195], v[12:15]
	v_mfma_f32_16x16x32_f16 v[16:19], v[144:147], v[192:195], v[16:19]
	v_mfma_f32_16x16x32_f16 v[56:59], v[148:151], v[164:167], v[56:59]
	v_mfma_f32_16x16x32_f16 v[52:55], v[156:159], v[164:167], v[52:55]
	v_mfma_f32_16x16x32_f16 v[40:43], v[148:151], v[172:175], v[40:43]
	v_mfma_f32_16x16x32_f16 v[36:39], v[156:159], v[172:175], v[36:39]
	v_mfma_f32_16x16x32_f16 v[24:27], v[148:151], v[180:183], v[24:27]
	v_mfma_f32_16x16x32_f16 v[20:23], v[156:159], v[180:183], v[20:23]
	v_mfma_f32_16x16x32_f16 v[4:7], v[148:151], v[188:191], v[4:7]
	v_mfma_f32_16x16x32_f16 v[8:11], v[156:159], v[188:191], v[8:11]
	v_mfma_f32_16x16x32_f16 v[56:59], v[152:155], v[168:171], v[56:59]
	v_mfma_f32_16x16x32_f16 v[52:55], v[160:163], v[168:171], v[52:55]
	v_mfma_f32_16x16x32_f16 v[40:43], v[152:155], v[176:179], v[40:43]
	v_mfma_f32_16x16x32_f16 v[36:39], v[160:163], v[176:179], v[36:39]
	v_mfma_f32_16x16x32_f16 v[24:27], v[152:155], v[184:187], v[24:27]
	v_mfma_f32_16x16x32_f16 v[20:23], v[160:163], v[184:187], v[20:23]
	v_mfma_f32_16x16x32_f16 v[4:7], v[152:155], v[192:195], v[4:7]
	v_mfma_f32_16x16x32_f16 v[8:11], v[160:163], v[192:195], v[8:11]
	s_barrier
	s_add_i32 s68, 0, 0x18000
	s_add_i32 s69, 0, 0x1c000
	v_add_u32_e32 v144, s68, v227
	v_add_u32_e32 v160, s69, v227
	ds_read_b128 v[132:135], v144
	ds_read_b128 v[136:139], v144 offset:1024
	ds_read_b128 v[140:143], v144 offset:2048
	ds_read_b128 v[144:147], v144 offset:3072
	ds_read_b128 v[148:151], v160
	ds_read_b128 v[152:155], v160 offset:1024
	ds_read_b128 v[156:159], v160 offset:2048
	ds_read_b128 v[160:163], v160 offset:3072
	s_add_u32 s44, s44, 0x80000
	s_addc_u32 s45, s45, 0
	s_mov_b32 m0, s54
	v_lshl_add_u64 v[222:223], s[44:45], 0, v[0:1]
	ds_read_b128 v[164:167], v228 offset:32768
	ds_read_b128 v[168:171], v228 offset:33792
	ds_read_b128 v[172:175], v228 offset:34816
	ds_read_b128 v[176:179], v228 offset:35840
	ds_read_b128 v[180:183], v228 offset:36864
	ds_read_b128 v[184:187], v228 offset:37888
	ds_read_b128 v[188:191], v228 offset:38912
	ds_read_b128 v[192:195], v228 offset:39936
	global_load_lds_dwordx4 v[222:223], off
	v_lshl_add_u64 v[222:223], s[44:45], 0, v[208:209]
	s_mov_b32 m0, s55
	s_nop 0
	global_load_lds_dwordx4 v[222:223], off
	s_waitcnt vmcnt(8)
	s_waitcnt lgkmcnt(0)
	s_barrier
	s_waitcnt lgkmcnt(0)
	v_mfma_f32_16x16x32_f16 v[128:131], v[132:135], v[164:167], v[128:131]
	v_mfma_f32_16x16x32_f16 v[124:127], v[140:143], v[164:167], v[124:127]
	v_mfma_f32_16x16x32_f16 v[112:115], v[132:135], v[172:175], v[112:115]
	v_mfma_f32_16x16x32_f16 v[108:111], v[140:143], v[172:175], v[108:111]
	v_mfma_f32_16x16x32_f16 v[96:99], v[132:135], v[180:183], v[96:99]
	v_mfma_f32_16x16x32_f16 v[92:95], v[140:143], v[180:183], v[92:95]
	v_mfma_f32_16x16x32_f16 v[80:83], v[132:135], v[188:191], v[80:83]
	v_mfma_f32_16x16x32_f16 v[76:79], v[140:143], v[188:191], v[76:79]
	v_mfma_f32_16x16x32_f16 v[128:131], v[136:139], v[168:171], v[128:131]
	v_mfma_f32_16x16x32_f16 v[124:127], v[144:147], v[168:171], v[124:127]
	v_mfma_f32_16x16x32_f16 v[112:115], v[136:139], v[176:179], v[112:115]
	v_mfma_f32_16x16x32_f16 v[108:111], v[144:147], v[176:179], v[108:111]
	v_mfma_f32_16x16x32_f16 v[96:99], v[136:139], v[184:187], v[96:99]
	v_mfma_f32_16x16x32_f16 v[92:95], v[144:147], v[184:187], v[92:95]
	v_mfma_f32_16x16x32_f16 v[80:83], v[136:139], v[192:195], v[80:83]
	v_mfma_f32_16x16x32_f16 v[76:79], v[144:147], v[192:195], v[76:79]
	v_mfma_f32_16x16x32_f16 v[120:123], v[148:151], v[164:167], v[120:123]
	v_mfma_f32_16x16x32_f16 v[116:119], v[156:159], v[164:167], v[116:119]
	v_mfma_f32_16x16x32_f16 v[104:107], v[148:151], v[172:175], v[104:107]
	v_mfma_f32_16x16x32_f16 v[100:103], v[156:159], v[172:175], v[100:103]
	v_mfma_f32_16x16x32_f16 v[88:91], v[148:151], v[180:183], v[88:91]
	v_mfma_f32_16x16x32_f16 v[84:87], v[156:159], v[180:183], v[84:87]
	v_mfma_f32_16x16x32_f16 v[68:71], v[148:151], v[188:191], v[68:71]
	v_mfma_f32_16x16x32_f16 v[72:75], v[156:159], v[188:191], v[72:75]
	v_mfma_f32_16x16x32_f16 v[120:123], v[152:155], v[168:171], v[120:123]
	v_mfma_f32_16x16x32_f16 v[116:119], v[160:163], v[168:171], v[116:119]
	v_mfma_f32_16x16x32_f16 v[104:107], v[152:155], v[176:179], v[104:107]
	v_mfma_f32_16x16x32_f16 v[100:103], v[160:163], v[176:179], v[100:103]
	v_mfma_f32_16x16x32_f16 v[88:91], v[152:155], v[184:187], v[88:91]
	v_mfma_f32_16x16x32_f16 v[84:87], v[160:163], v[184:187], v[84:87]
	v_mfma_f32_16x16x32_f16 v[68:71], v[152:155], v[192:195], v[68:71]
	v_mfma_f32_16x16x32_f16 v[72:75], v[160:163], v[192:195], v[72:75]
	s_barrier
; #define PG8_STAGE(bufoff, gbase, voff) do { _Pragma("unroll") for (int _i = 0; _i < 2; ++_i) \
;         __builtin_amdgcn_global_load_lds((const unsigned*)((const char*)(gbase) + (voff)[_i]), (LAS unsigned*)(lds + (bufoff) + ldsw + _i * 8192), 16, 0, 0); } while (0)
; #define PG8_LDA(dst, b, h) do { _Pragma("unroll") for (int m = 0; m < 4; ++m) _Pragma("unroll") for (int k = 0; k < 2; ++k) dst[m][k] = *(const LAS bf16x8*)(lds + PG8_SA(b, h) + aoff + m * 2048 + k * 1024); } while (0)
; #define PG8_WAIT_V(n) asm volatile("s_waitcnt vmcnt(" #n ")" ::: "memory")
; #define PG8_WAIT_L(n) asm volatile("s_waitcnt lgkmcnt(" #n ")" ::: "memory")
; #define PG8_BAR __builtin_amdgcn_s_barrier()
; #define PG8_SCHED __builtin_amdgcn_sched_barrier(0)
; template <class Epi, class Sched, bool FUSED = false, bool APERM = false>
; __device__ __forceinline__ void gemm_phase(int wid_s, LAS unsigned char* lds, const Gemm g, const Sched& S, const Epi& E) {
;     ...
;             PG8_LDA(At, 1, 1); PG8_STAGE(PG8_SB(1, 0), b3, voffB); PG8_STAGE(PG8_SB(1, 1), b3 + hstep, voffB); PG8_STAGE(PG8_SA(1, 0), a3, voffA);
;             PG8_WAIT_V(8); PG8_WAIT_L(0); PG8_BAR; PG8_MMA(1, 0, At, B0); PG8_MMA(1, 1, At, B1); PG8_BAR; PG8_SCHED;
;         }
	s_add_i32 s44, s68, s51
	v_lshl_add_u64 v[214:215], v[214:215], 0, s[12:13]
	s_mov_b32 m0, s44
	ds_read_b128 v[164:167], v228 offset:49152
	ds_read_b128 v[168:171], v228 offset:50176
	ds_read_b128 v[172:175], v228 offset:51200
	ds_read_b128 v[176:179], v228 offset:52224
	ds_read_b128 v[180:183], v228 offset:53248
	ds_read_b128 v[184:187], v228 offset:54272
	ds_read_b128 v[188:191], v228 offset:55296
	ds_read_b128 v[192:195], v228 offset:56320
	global_load_lds_dwordx4 v[214:215], off
	s_add_i32 m0, s44, 0x2000
	s_add_u32 s42, s42, 0x80080
	v_lshl_add_u64 v[214:215], v[216:217], 0, s[12:13]
	s_addc_u32 s43, s43, 0
	s_add_i32 s44, s69, s51
	global_load_lds_dwordx4 v[214:215], off
	v_lshl_add_u64 v[214:215], s[42:43], 0, v[0:1]
	s_mov_b32 m0, s44
	s_nop 0
	global_load_lds_dwordx4 v[214:215], off
	v_lshl_add_u64 v[214:215], s[42:43], 0, v[208:209]
	s_add_i32 m0, s44, 0x2000
	s_nop 0
	global_load_lds_dwordx4 v[214:215], off
	v_lshl_add_u64 v[214:215], v[218:219], 0, s[12:13]
	s_mov_b32 m0, s59
	s_nop 0
	global_load_lds_dwordx4 v[214:215], off
	v_lshl_add_u64 v[214:215], v[220:221], 0, s[12:13]
	s_mov_b32 m0, s60
	s_nop 0
	global_load_lds_dwordx4 v[214:215], off
	s_waitcnt vmcnt(8)
	s_waitcnt lgkmcnt(0)
	s_barrier
	s_waitcnt lgkmcnt(0)
	v_mfma_f32_16x16x32_f16 v[64:67], v[132:135], v[164:167], v[64:67]
	v_mfma_f32_16x16x32_f16 v[60:63], v[140:143], v[164:167], v[60:63]
	v_mfma_f32_16x16x32_f16 v[48:51], v[132:135], v[172:175], v[48:51]
	v_mfma_f32_16x16x32_f16 v[44:47], v[140:143], v[172:175], v[44:47]
	v_mfma_f32_16x16x32_f16 v[32:35], v[132:135], v[180:183], v[32:35]
	v_mfma_f32_16x16x32_f16 v[28:31], v[140:143], v[180:183], v[28:31]
	v_mfma_f32_16x16x32_f16 v[12:15], v[132:135], v[188:191], v[12:15]
	v_mfma_f32_16x16x32_f16 v[16:19], v[140:143], v[188:191], v[16:19]
	v_mfma_f32_16x16x32_f16 v[64:67], v[136:139], v[168:171], v[64:67]
	v_mfma_f32_16x16x32_f16 v[60:63], v[144:147], v[168:171], v[60:63]
	v_mfma_f32_16x16x32_f16 v[48:51], v[136:139], v[176:179], v[48:51]
	v_mfma_f32_16x16x32_f16 v[44:47], v[144:147], v[176:179], v[44:47]
	v_mfma_f32_16x16x32_f16 v[32:35], v[136:139], v[184:187], v[32:35]
	v_mfma_f32_16x16x32_f16 v[28:31], v[144:147], v[184:187], v[28:31]
	v_mfma_f32_16x16x32_f16 v[12:15], v[136:139], v[192:195], v[12:15]
	v_mfma_f32_16x16x32_f16 v[16:19], v[144:147], v[192:195], v[16:19]
	v_mfma_f32_16x16x32_f16 v[56:59], v[148:151], v[164:167], v[56:59]
	v_mfma_f32_16x16x32_f16 v[52:55], v[156:159], v[164:167], v[52:55]
	v_mfma_f32_16x16x32_f16 v[40:43], v[148:151], v[172:175], v[40:43]
	v_mfma_f32_16x16x32_f16 v[36:39], v[156:159], v[172:175], v[36:39]
	v_mfma_f32_16x16x32_f16 v[24:27], v[148:151], v[180:183], v[24:27]
	v_mfma_f32_16x16x32_f16 v[20:23], v[156:159], v[180:183], v[20:23]
	v_mfma_f32_16x16x32_f16 v[4:7], v[148:151], v[188:191], v[4:7]
	v_mfma_f32_16x16x32_f16 v[8:11], v[156:159], v[188:191], v[8:11]
	v_mfma_f32_16x16x32_f16 v[56:59], v[152:155], v[168:171], v[56:59]
	v_mfma_f32_16x16x32_f16 v[52:55], v[160:163], v[168:171], v[52:55]
	v_mfma_f32_16x16x32_f16 v[40:43], v[152:155], v[176:179], v[40:43]
	v_mfma_f32_16x16x32_f16 v[36:39], v[160:163], v[176:179], v[36:39]
	v_mfma_f32_16x16x32_f16 v[24:27], v[152:155], v[184:187], v[24:27]
	v_mfma_f32_16x16x32_f16 v[20:23], v[160:163], v[184:187], v[20:23]
	v_mfma_f32_16x16x32_f16 v[4:7], v[152:155], v[192:195], v[4:7]
	v_mfma_f32_16x16x32_f16 v[8:11], v[160:163], v[192:195], v[8:11]
	s_barrier
	s_add_i32 s67, s67, 2
	s_add_u32 s35, s35, 0x100
	s_addc_u32 s66, s66, 0
	s_add_u32 s40, s40, 0x100
	s_addc_u32 s41, s41, 0
	s_cmp_gt_u32 s67, 29
	s_cbranch_scc0 .LBB0_145
	s_and_b64 vcc, exec, s[16:17]
	s_cbranch_vccz .LBB0_148
	s_barrier

; #define PG8_STAGE(bufoff, gbase, voff) do { _Pragma("unroll") for (int _i = 0; _i < 2; ++_i) \
;         __builtin_amdgcn_global_load_lds((const unsigned*)((const char*)(gbase) + (voff)[_i]), (LAS unsigned*)(lds + (bufoff) + ldsw + _i * 8192), 16, 0, 0); } while (0)
; #define PG8_LDA(dst, b, h) do { _Pragma("unroll") for (int m = 0; m < 4; ++m) _Pragma("unroll") for (int k = 0; k < 2; ++k) dst[m][k] = *(const LAS bf16x8*)(lds + PG8_SA(b, h) + aoff + m * 2048 + k * 1024); } while (0)
; #define PG8_LDB(dst, b, h) do { _Pragma("unroll") for (int n = 0; n < 2; ++n) _Pragma("unroll") for (int k = 0; k < 2; ++k) dst[n][k] = *(const LAS bf16x8*)(lds + PG8_SB(b, h) + boff + n * 2048 + k * 1024); } while (0)
; #define PG8_WAIT_V(n) asm volatile("s_waitcnt vmcnt(" #n ")" ::: "memory")
; #define PG8_WAIT_L(n) asm volatile("s_waitcnt lgkmcnt(" #n ")" ::: "memory")
; #define PG8_BAR __builtin_amdgcn_s_barrier()
; #define PG8_SCHED __builtin_amdgcn_sched_barrier(0)
; template <class Epi, class Sched, bool FUSED = false, bool APERM = false>
; __device__ __forceinline__ void gemm_phase(int wid_s, LAS unsigned char* lds, const Gemm g, const Sched& S, const Epi& E) {
;     ...
;             const bool last = (t == nt - 2);
;             const char* a1 = cA + (size_t)(t + 1) * kstep;
;             const char* a2 = last ? nA : cA + (size_t)(t + 2) * kstep; const char* b2 = last ? nB : cB + (size_t)(t + 2) * kstep;
;             const char* a3 = a2 + kstep; const char* b3 = b2 + kstep;
;             if (last && has_next) S.a_ready(nxt);
;             PG8_LDB(B0, 0, 0); PG8_LDB(B1, 0, 1); PG8_SCHED; PG8_LDA(At, 0, 0); PG8_STAGE(PG8_SA(1, 1), a1 + hstep, voffA);
;             PG8_WAIT_V(8); PG8_WAIT_L(0); PG8_BAR; PG8_MMA(0, 0, At, B0); PG8_MMA(0, 1, At, B1); PG8_BAR; PG8_SCHED;
;             PG8_LDA(At, 0, 1); PG8_STAGE(PG8_SB(0, 0), b2, voffB); PG8_STAGE(PG8_SB(0, 1), b2 + hstep, voffB); PG8_STAGE(PG8_SA(0, 0), a2, voffA);
.LBB0_342:
	s_add_u32 s38, s36, 0xfff80080
	s_addc_u32 s39, s37, -1
	s_add_i32 s64, 0, 0x10000
	s_cmp_eq_u32 s63, 28
	s_cselect_b32 s41, s1, s39
	s_cselect_b32 s40, s23, s38
	s_cselect_b32 s39, s25, s62
	s_cselect_b32 s38, s35, s61
	s_add_i32 s66, 0, 0x14000
	v_add_u32_e32 v144, s64, v227
	v_add_u32_e32 v160, s66, v227
	ds_read_b128 v[132:135], v144
	ds_read_b128 v[136:139], v144 offset:1024
	ds_read_b128 v[140:143], v144 offset:2048
	ds_read_b128 v[144:147], v144 offset:3072
	ds_read_b128 v[148:151], v160
	ds_read_b128 v[152:155], v160 offset:1024
	ds_read_b128 v[156:159], v160 offset:2048
	ds_read_b128 v[160:163], v160 offset:3072
	v_lshl_add_u64 v[214:215], s[36:37], 0, v[212:213]
	s_add_i32 m0, s48, 0xc000
	ds_read_b128 v[164:167], v228
	ds_read_b128 v[168:171], v228 offset:1024
	ds_read_b128 v[172:175], v228 offset:2048
	ds_read_b128 v[176:179], v228 offset:3072
	ds_read_b128 v[180:183], v228 offset:4096
	ds_read_b128 v[184:187], v228 offset:5120
	ds_read_b128 v[188:191], v228 offset:6144
	ds_read_b128 v[192:195], v228 offset:7168
	global_load_lds_dwordx4 v[214:215], off
	v_lshl_add_u64 v[214:215], s[36:37], 0, v[210:211]
	s_add_i32 m0, s48, 0xe000
	s_nop 0
	global_load_lds_dwordx4 v[214:215], off
	s_waitcnt vmcnt(8)
	s_waitcnt lgkmcnt(0)
	s_barrier
	s_waitcnt lgkmcnt(0)
	v_mfma_f32_16x16x32_f16 v[128:131], v[132:135], v[164:167], v[128:131]
	v_mfma_f32_16x16x32_f16 v[124:127], v[140:143], v[164:167], v[124:127]
	v_mfma_f32_16x16x32_f16 v[112:115], v[132:135], v[172:175], v[112:115]
	v_mfma_f32_16x16x32_f16 v[108:111], v[140:143], v[172:175], v[108:111]
	v_mfma_f32_16x16x32_f16 v[96:99], v[132:135], v[180:183], v[96:99]
	v_mfma_f32_16x16x32_f16 v[92:95], v[140:143], v[180:183], v[92:95]
	v_mfma_f32_16x16x32_f16 v[80:83], v[132:135], v[188:191], v[80:83]
	v_mfma_f32_16x16x32_f16 v[76:79], v[140:143], v[188:191], v[76:79]
	v_mfma_f32_16x16x32_f16 v[128:131], v[136:139], v[168:171], v[128:131]
	v_mfma_f32_16x16x32_f16 v[124:127], v[144:147], v[168:171], v[124:127]
	v_mfma_f32_16x16x32_f16 v[112:115], v[136:139], v[176:179], v[112:115]
	v_mfma_f32_16x16x32_f16 v[108:111], v[144:147], v[176:179], v[108:111]
	v_mfma_f32_16x16x32_f16 v[96:99], v[136:139], v[184:187], v[96:99]
	v_mfma_f32_16x16x32_f16 v[92:95], v[144:147], v[184:187], v[92:95]
	v_mfma_f32_16x16x32_f16 v[80:83], v[136:139], v[192:195], v[80:83]
	v_mfma_f32_16x16x32_f16 v[76:79], v[144:147], v[192:195], v[76:79]
	v_mfma_f32_16x16x32_f16 v[120:123], v[148:151], v[164:167], v[120:123]
	v_mfma_f32_16x16x32_f16 v[116:119], v[156:159], v[164:167], v[116:119]
	v_mfma_f32_16x16x32_f16 v[104:107], v[148:151], v[172:175], v[104:107]
	v_mfma_f32_16x16x32_f16 v[100:103], v[156:159], v[172:175], v[100:103]
	v_mfma_f32_16x16x32_f16 v[88:91], v[148:151], v[180:183], v[88:91]
	v_mfma_f32_16x16x32_f16 v[84:87], v[156:159], v[180:183], v[84:87]
	v_mfma_f32_16x16x32_f16 v[68:71], v[148:151], v[188:191], v[68:71]
	v_mfma_f32_16x16x32_f16 v[72:75], v[156:159], v[188:191], v[72:75]
	v_mfma_f32_16x16x32_f16 v[120:123], v[152:155], v[168:171], v[120:123]
	v_mfma_f32_16x16x32_f16 v[116:119], v[160:163], v[168:171], v[116:119]
	v_mfma_f32_16x16x32_f16 v[104:107], v[152:155], v[176:179], v[104:107]
	v_mfma_f32_16x16x32_f16 v[100:103], v[160:163], v[176:179], v[100:103]
	v_mfma_f32_16x16x32_f16 v[88:91], v[152:155], v[184:187], v[88:91]
	v_mfma_f32_16x16x32_f16 v[84:87], v[160:163], v[184:187], v[84:87]
	v_mfma_f32_16x16x32_f16 v[68:71], v[152:155], v[192:195], v[68:71]
	v_mfma_f32_16x16x32_f16 v[72:75], v[160:163], v[192:195], v[72:75]
	s_barrier
	s_add_i32 s64, s64, s47
	v_lshl_add_u64 v[214:215], s[38:39], 0, v[0:1]
	s_mov_b32 m0, s64
	ds_read_b128 v[164:167], v228 offset:16384
	ds_read_b128 v[168:171], v228 offset:17408
	ds_read_b128 v[172:175], v228 offset:18432
	ds_read_b128 v[176:179], v228 offset:19456
	ds_read_b128 v[180:183], v228 offset:20480
	ds_read_b128 v[184:187], v228 offset:21504
	ds_read_b128 v[188:191], v228 offset:22528
	ds_read_b128 v[192:195], v228 offset:23552
	global_load_lds_dwordx4 v[214:215], off
	s_add_i32 m0, s64, 0x2000
	s_add_u32 s64, s38, 0x80000
	v_lshl_add_u64 v[216:217], s[38:39], 0, v[208:209]
	s_addc_u32 s65, s39, 0
	s_add_i32 s66, s66, s47
	global_load_lds_dwordx4 v[216:217], off
	v_lshl_add_u64 v[218:219], s[64:65], 0, v[0:1]
	s_mov_b32 m0, s66
	v_lshl_add_u64 v[220:221], s[40:41], 0, v[208:209]
	global_load_lds_dwordx4 v[218:219], off
	v_lshl_add_u64 v[218:219], s[64:65], 0, v[208:209]
	s_add_i32 m0, s66, 0x2000
	s_nop 0
	global_load_lds_dwordx4 v[218:219], off
	v_lshl_add_u64 v[218:219], s[40:41], 0, v[0:1]
	s_mov_b32 m0, s48
	s_nop 0
	global_load_lds_dwordx4 v[218:219], off
	s_mov_b32 m0, s49
	s_nop 0
	global_load_lds_dwordx4 v[220:221], off
	s_waitcnt vmcnt(8)
	s_waitcnt lgkmcnt(0)
	s_barrier
; #define PG8_STAGE(bufoff, gbase, voff) do { _Pragma("unroll") for (int _i = 0; _i < 2; ++_i) \
;         __builtin_amdgcn_global_load_lds((const unsigned*)((const char*)(gbase) + (voff)[_i]), (LAS unsigned*)(lds + (bufoff) + ldsw + _i * 8192), 16, 0, 0); } while (0)
; #define PG8_LDA(dst, b, h) do { _Pragma("unroll") for (int m = 0; m < 4; ++m) _Pragma("unroll") for (int k = 0; k < 2; ++k) dst[m][k] = *(const LAS bf16x8*)(lds + PG8_SA(b, h) + aoff + m * 2048 + k * 1024); } while (0)
; #define PG8_LDB(dst, b, h) do { _Pragma("unroll") for (int n = 0; n < 2; ++n) _Pragma("unroll") for (int k = 0; k < 2; ++k) dst[n][k] = *(const LAS bf16x8*)(lds + PG8_SB(b, h) + boff + n * 2048 + k * 1024); } while (0)
; #define PG8_WAIT_V(n) asm volatile("s_waitcnt vmcnt(" #n ")" ::: "memory")
; #define PG8_WAIT_L(n) asm volatile("s_waitcnt lgkmcnt(" #n ")" ::: "memory")
; #define PG8_BAR __builtin_amdgcn_s_barrier()
; #define PG8_SCHED __builtin_amdgcn_sched_barrier(0)
; template <class Epi, class Sched, bool FUSED = false, bool APERM = false>
; __device__ __forceinline__ void gemm_phase(int wid_s, LAS unsigned char* lds, const Gemm g, const Sched& S, const Epi& E) {
;     ...
;             PG8_WAIT_V(8); PG8_WAIT_L(0); PG8_BAR; PG8_MMA(1, 0, At, B0); PG8_MMA(1, 1, At, B1); PG8_BAR; PG8_SCHED;
;             PG8_LDB(B0, 1, 0); PG8_LDB(B1, 1, 1); PG8_SCHED; PG8_LDA(At, 1, 0); PG8_STAGE(PG8_SA(0, 1), a2 + hstep, voffA);
;             PG8_WAIT_V(8); PG8_WAIT_L(0); PG8_BAR; PG8_MMA(0, 0, At, B0); PG8_MMA(0, 1, At, B1); PG8_BAR; PG8_SCHED;
	s_waitcnt lgkmcnt(0)
	v_mfma_f32_16x16x32_f16 v[64:67], v[132:135], v[164:167], v[64:67]
	v_mfma_f32_16x16x32_f16 v[60:63], v[140:143], v[164:167], v[60:63]
	v_mfma_f32_16x16x32_f16 v[48:51], v[132:135], v[172:175], v[48:51]
	v_mfma_f32_16x16x32_f16 v[44:47], v[140:143], v[172:175], v[44:47]
	v_mfma_f32_16x16x32_f16 v[32:35], v[132:135], v[180:183], v[32:35]
	v_mfma_f32_16x16x32_f16 v[28:31], v[140:143], v[180:183], v[28:31]
	v_mfma_f32_16x16x32_f16 v[12:15], v[132:135], v[188:191], v[12:15]
	v_mfma_f32_16x16x32_f16 v[16:19], v[140:143], v[188:191], v[16:19]
	v_mfma_f32_16x16x32_f16 v[64:67], v[136:139], v[168:171], v[64:67]
	v_mfma_f32_16x16x32_f16 v[60:63], v[144:147], v[168:171], v[60:63]
	v_mfma_f32_16x16x32_f16 v[48:51], v[136:139], v[176:179], v[48:51]
	v_mfma_f32_16x16x32_f16 v[44:47], v[144:147], v[176:179], v[44:47]
	v_mfma_f32_16x16x32_f16 v[32:35], v[136:139], v[184:187], v[32:35]
	v_mfma_f32_16x16x32_f16 v[28:31], v[144:147], v[184:187], v[28:31]
	v_mfma_f32_16x16x32_f16 v[12:15], v[136:139], v[192:195], v[12:15]
	v_mfma_f32_16x16x32_f16 v[16:19], v[144:147], v[192:195], v[16:19]
	v_mfma_f32_16x16x32_f16 v[56:59], v[148:151], v[164:167], v[56:59]
	v_mfma_f32_16x16x32_f16 v[52:55], v[156:159], v[164:167], v[52:55]
	v_mfma_f32_16x16x32_f16 v[40:43], v[148:151], v[172:175], v[40:43]
	v_mfma_f32_16x16x32_f16 v[36:39], v[156:159], v[172:175], v[36:39]
	v_mfma_f32_16x16x32_f16 v[24:27], v[148:151], v[180:183], v[24:27]
	v_mfma_f32_16x16x32_f16 v[20:23], v[156:159], v[180:183], v[20:23]
	v_mfma_f32_16x16x32_f16 v[4:7], v[148:151], v[188:191], v[4:7]
	v_mfma_f32_16x16x32_f16 v[8:11], v[156:159], v[188:191], v[8:11]
	v_mfma_f32_16x16x32_f16 v[56:59], v[152:155], v[168:171], v[56:59]
	v_mfma_f32_16x16x32_f16 v[52:55], v[160:163], v[168:171], v[52:55]
	v_mfma_f32_16x16x32_f16 v[40:43], v[152:155], v[176:179], v[40:43]
	v_mfma_f32_16x16x32_f16 v[36:39], v[160:163], v[176:179], v[36:39]
	v_mfma_f32_16x16x32_f16 v[24:27], v[152:155], v[184:187], v[24:27]
	v_mfma_f32_16x16x32_f16 v[20:23], v[160:163], v[184:187], v[20:23]
	v_mfma_f32_16x16x32_f16 v[4:7], v[152:155], v[192:195], v[4:7]
	v_mfma_f32_16x16x32_f16 v[8:11], v[160:163], v[192:195], v[8:11]
	s_barrier
	s_add_i32 s64, 0, 0x18000
	s_add_i32 s65, 0, 0x1c000
	v_add_u32_e32 v144, s64, v227
	v_add_u32_e32 v160, s65, v227
	ds_read_b128 v[132:135], v144
	ds_read_b128 v[136:139], v144 offset:1024
	ds_read_b128 v[140:143], v144 offset:2048
	ds_read_b128 v[144:147], v144 offset:3072
	ds_read_b128 v[148:151], v160
	ds_read_b128 v[152:155], v160 offset:1024
	ds_read_b128 v[156:159], v160 offset:2048
	ds_read_b128 v[160:163], v160 offset:3072
	s_add_u32 s40, s40, 0x80000
	s_addc_u32 s41, s41, 0
	s_mov_b32 m0, s50
	v_lshl_add_u64 v[222:223], s[40:41], 0, v[0:1]
	ds_read_b128 v[164:167], v228 offset:32768
	ds_read_b128 v[168:171], v228 offset:33792
	ds_read_b128 v[172:175], v228 offset:34816
	ds_read_b128 v[176:179], v228 offset:35840
	ds_read_b128 v[180:183], v228 offset:36864
	ds_read_b128 v[184:187], v228 offset:37888
	ds_read_b128 v[188:191], v228 offset:38912
	ds_read_b128 v[192:195], v228 offset:39936
	global_load_lds_dwordx4 v[222:223], off
	v_lshl_add_u64 v[222:223], s[40:41], 0, v[208:209]
	s_mov_b32 m0, s51
	s_nop 0
	global_load_lds_dwordx4 v[222:223], off
	s_waitcnt vmcnt(8)
	s_waitcnt lgkmcnt(0)
	s_barrier
	s_waitcnt lgkmcnt(0)
	v_mfma_f32_16x16x32_f16 v[128:131], v[132:135], v[164:167], v[128:131]
	v_mfma_f32_16x16x32_f16 v[124:127], v[140:143], v[164:167], v[124:127]
	v_mfma_f32_16x16x32_f16 v[112:115], v[132:135], v[172:175], v[112:115]
	v_mfma_f32_16x16x32_f16 v[108:111], v[140:143], v[172:175], v[108:111]
	v_mfma_f32_16x16x32_f16 v[96:99], v[132:135], v[180:183], v[96:99]
	v_mfma_f32_16x16x32_f16 v[92:95], v[140:143], v[180:183], v[92:95]
	v_mfma_f32_16x16x32_f16 v[80:83], v[132:135], v[188:191], v[80:83]
	v_mfma_f32_16x16x32_f16 v[76:79], v[140:143], v[188:191], v[76:79]
	v_mfma_f32_16x16x32_f16 v[128:131], v[136:139], v[168:171], v[128:131]
	v_mfma_f32_16x16x32_f16 v[124:127], v[144:147], v[168:171], v[124:127]
	v_mfma_f32_16x16x32_f16 v[112:115], v[136:139], v[176:179], v[112:115]
	v_mfma_f32_16x16x32_f16 v[108:111], v[144:147], v[176:179], v[108:111]
	v_mfma_f32_16x16x32_f16 v[96:99], v[136:139], v[184:187], v[96:99]
	v_mfma_f32_16x16x32_f16 v[92:95], v[144:147], v[184:187], v[92:95]
	v_mfma_f32_16x16x32_f16 v[80:83], v[136:139], v[192:195], v[80:83]
	v_mfma_f32_16x16x32_f16 v[76:79], v[144:147], v[192:195], v[76:79]
	v_mfma_f32_16x16x32_f16 v[120:123], v[148:151], v[164:167], v[120:123]
	v_mfma_f32_16x16x32_f16 v[116:119], v[156:159], v[164:167], v[116:119]
	v_mfma_f32_16x16x32_f16 v[104:107], v[148:151], v[172:175], v[104:107]
	v_mfma_f32_16x16x32_f16 v[100:103], v[156:159], v[172:175], v[100:103]
	v_mfma_f32_16x16x32_f16 v[88:91], v[148:151], v[180:183], v[88:91]
	v_mfma_f32_16x16x32_f16 v[84:87], v[156:159], v[180:183], v[84:87]
	v_mfma_f32_16x16x32_f16 v[68:71], v[148:151], v[188:191], v[68:71]
	v_mfma_f32_16x16x32_f16 v[72:75], v[156:159], v[188:191], v[72:75]
	v_mfma_f32_16x16x32_f16 v[120:123], v[152:155], v[168:171], v[120:123]
	v_mfma_f32_16x16x32_f16 v[116:119], v[160:163], v[168:171], v[116:119]
	v_mfma_f32_16x16x32_f16 v[104:107], v[152:155], v[176:179], v[104:107]
	v_mfma_f32_16x16x32_f16 v[100:103], v[160:163], v[176:179], v[100:103]
	v_mfma_f32_16x16x32_f16 v[88:91], v[152:155], v[184:187], v[88:91]
	v_mfma_f32_16x16x32_f16 v[84:87], v[160:163], v[184:187], v[84:87]
	v_mfma_f32_16x16x32_f16 v[68:71], v[152:155], v[192:195], v[68:71]
	v_mfma_f32_16x16x32_f16 v[72:75], v[160:163], v[192:195], v[72:75]
	s_barrier
; #define PG8_STAGE(bufoff, gbase, voff) do { _Pragma("unroll") for (int _i = 0; _i < 2; ++_i) \
;         __builtin_amdgcn_global_load_lds((const unsigned*)((const char*)(gbase) + (voff)[_i]), (LAS unsigned*)(lds + (bufoff) + ldsw + _i * 8192), 16, 0, 0); } while (0)
; #define PG8_LDA(dst, b, h) do { _Pragma("unroll") for (int m = 0; m < 4; ++m) _Pragma("unroll") for (int k = 0; k < 2; ++k) dst[m][k] = *(const LAS bf16x8*)(lds + PG8_SA(b, h) + aoff + m * 2048 + k * 1024); } while (0)
; #define PG8_WAIT_V(n) asm volatile("s_waitcnt vmcnt(" #n ")" ::: "memory")
; #define PG8_WAIT_L(n) asm volatile("s_waitcnt lgkmcnt(" #n ")" ::: "memory")
; #define PG8_BAR __builtin_amdgcn_s_barrier()
; #define PG8_SCHED __builtin_amdgcn_sched_barrier(0)
; template <class Epi, class Sched, bool FUSED = false, bool APERM = false>
; __device__ __forceinline__ void gemm_phase(int wid_s, LAS unsigned char* lds, const Gemm g, const Sched& S, const Epi& E) {
;     ...
;             PG8_LDA(At, 1, 1); PG8_STAGE(PG8_SB(1, 0), b3, voffB); PG8_STAGE(PG8_SB(1, 1), b3 + hstep, voffB); PG8_STAGE(PG8_SA(1, 0), a3, voffA);
;             PG8_WAIT_V(8); PG8_WAIT_L(0); PG8_BAR; PG8_MMA(1, 0, At, B0); PG8_MMA(1, 1, At, B1); PG8_BAR; PG8_SCHED;
;         }
	s_add_i32 s40, s64, s47
	v_lshl_add_u64 v[214:215], v[214:215], 0, s[12:13]
	s_mov_b32 m0, s40
	ds_read_b128 v[164:167], v228 offset:49152
	ds_read_b128 v[168:171], v228 offset:50176
	ds_read_b128 v[172:175], v228 offset:51200
	ds_read_b128 v[176:179], v228 offset:52224
	ds_read_b128 v[180:183], v228 offset:53248
	ds_read_b128 v[184:187], v228 offset:54272
	ds_read_b128 v[188:191], v228 offset:55296
	ds_read_b128 v[192:195], v228 offset:56320
	global_load_lds_dwordx4 v[214:215], off
	s_add_i32 m0, s40, 0x2000
	s_add_u32 s38, s38, 0x80080
	v_lshl_add_u64 v[214:215], v[216:217], 0, s[12:13]
	s_addc_u32 s39, s39, 0
	s_add_i32 s40, s65, s47
	global_load_lds_dwordx4 v[214:215], off
	v_lshl_add_u64 v[214:215], s[38:39], 0, v[0:1]
	s_mov_b32 m0, s40
	s_nop 0
	global_load_lds_dwordx4 v[214:215], off
	v_lshl_add_u64 v[214:215], s[38:39], 0, v[208:209]
	s_add_i32 m0, s40, 0x2000
	s_nop 0
	global_load_lds_dwordx4 v[214:215], off
	v_lshl_add_u64 v[214:215], v[218:219], 0, s[12:13]
	s_mov_b32 m0, s55
	s_nop 0
	global_load_lds_dwordx4 v[214:215], off
	v_lshl_add_u64 v[214:215], v[220:221], 0, s[12:13]
	s_mov_b32 m0, s56
	s_nop 0
	global_load_lds_dwordx4 v[214:215], off
	s_waitcnt vmcnt(8)
	s_waitcnt lgkmcnt(0)
	s_barrier
	s_waitcnt lgkmcnt(0)
	v_mfma_f32_16x16x32_f16 v[64:67], v[132:135], v[164:167], v[64:67]
	v_mfma_f32_16x16x32_f16 v[60:63], v[140:143], v[164:167], v[60:63]
	v_mfma_f32_16x16x32_f16 v[48:51], v[132:135], v[172:175], v[48:51]
	v_mfma_f32_16x16x32_f16 v[44:47], v[140:143], v[172:175], v[44:47]
	v_mfma_f32_16x16x32_f16 v[32:35], v[132:135], v[180:183], v[32:35]
	v_mfma_f32_16x16x32_f16 v[28:31], v[140:143], v[180:183], v[28:31]
	v_mfma_f32_16x16x32_f16 v[12:15], v[132:135], v[188:191], v[12:15]
	v_mfma_f32_16x16x32_f16 v[16:19], v[140:143], v[188:191], v[16:19]
	v_mfma_f32_16x16x32_f16 v[64:67], v[136:139], v[168:171], v[64:67]
	v_mfma_f32_16x16x32_f16 v[60:63], v[144:147], v[168:171], v[60:63]
	v_mfma_f32_16x16x32_f16 v[48:51], v[136:139], v[176:179], v[48:51]
	v_mfma_f32_16x16x32_f16 v[44:47], v[144:147], v[176:179], v[44:47]
	v_mfma_f32_16x16x32_f16 v[32:35], v[136:139], v[184:187], v[32:35]
	v_mfma_f32_16x16x32_f16 v[28:31], v[144:147], v[184:187], v[28:31]
	v_mfma_f32_16x16x32_f16 v[12:15], v[136:139], v[192:195], v[12:15]
	v_mfma_f32_16x16x32_f16 v[16:19], v[144:147], v[192:195], v[16:19]
	v_mfma_f32_16x16x32_f16 v[56:59], v[148:151], v[164:167], v[56:59]
	v_mfma_f32_16x16x32_f16 v[52:55], v[156:159], v[164:167], v[52:55]
	v_mfma_f32_16x16x32_f16 v[40:43], v[148:151], v[172:175], v[40:43]
	v_mfma_f32_16x16x32_f16 v[36:39], v[156:159], v[172:175], v[36:39]
	v_mfma_f32_16x16x32_f16 v[24:27], v[148:151], v[180:183], v[24:27]
	v_mfma_f32_16x16x32_f16 v[20:23], v[156:159], v[180:183], v[20:23]
	v_mfma_f32_16x16x32_f16 v[4:7], v[148:151], v[188:191], v[4:7]
	v_mfma_f32_16x16x32_f16 v[8:11], v[156:159], v[188:191], v[8:11]
	v_mfma_f32_16x16x32_f16 v[56:59], v[152:155], v[168:171], v[56:59]
	v_mfma_f32_16x16x32_f16 v[52:55], v[160:163], v[168:171], v[52:55]
	v_mfma_f32_16x16x32_f16 v[40:43], v[152:155], v[176:179], v[40:43]
	v_mfma_f32_16x16x32_f16 v[36:39], v[160:163], v[176:179], v[36:39]
	v_mfma_f32_16x16x32_f16 v[24:27], v[152:155], v[184:187], v[24:27]
	v_mfma_f32_16x16x32_f16 v[20:23], v[160:163], v[184:187], v[20:23]
	v_mfma_f32_16x16x32_f16 v[4:7], v[152:155], v[192:195], v[4:7]
	v_mfma_f32_16x16x32_f16 v[8:11], v[160:163], v[192:195], v[8:11]
	s_barrier
	s_add_i32 s63, s63, 2
	s_add_u32 s61, s61, 0x100
	s_addc_u32 s62, s62, 0
	s_add_u32 s36, s36, 0x100
	s_addc_u32 s37, s37, 0
	s_cmp_gt_u32 s63, 29
	s_cbranch_scc0 .LBB0_342
	s_and_b64 vcc, exec, s[14:15]
	s_cbranch_vccz .LBB0_345
	s_barrier

; #define PG8_STAGE(bufoff, gbase, voff) do { _Pragma("unroll") for (int _i = 0; _i < 2; ++_i) \
;         __builtin_amdgcn_global_load_lds((const unsigned*)((const char*)(gbase) + (voff)[_i]), (LAS unsigned*)(lds + (bufoff) + ldsw + _i * 8192), 16, 0, 0); } while (0)
; #define PG8_LDA(dst, b, h) do { _Pragma("unroll") for (int m = 0; m < 4; ++m) _Pragma("unroll") for (int k = 0; k < 2; ++k) dst[m][k] = *(const LAS bf16x8*)(lds + PG8_SA(b, h) + aoff + m * 2048 + k * 1024); } while (0)
; #define PG8_LDB(dst, b, h) do { _Pragma("unroll") for (int n = 0; n < 2; ++n) _Pragma("unroll") for (int k = 0; k < 2; ++k) dst[n][k] = *(const LAS bf16x8*)(lds + PG8_SB(b, h) + boff + n * 2048 + k * 1024); } while (0)
; #define PG8_WAIT_V(n) asm volatile("s_waitcnt vmcnt(" #n ")" ::: "memory")
; #define PG8_WAIT_L(n) asm volatile("s_waitcnt lgkmcnt(" #n ")" ::: "memory")
; #define PG8_BAR __builtin_amdgcn_s_barrier()
; #define PG8_SCHED __builtin_amdgcn_sched_barrier(0)
; template <class Epi, class Sched, bool FUSED = false, bool APERM = false>
; __device__ __forceinline__ void gemm_phase(int wid_s, LAS unsigned char* lds, const Gemm g, const Sched& S, const Epi& E) {
;     ...
;             const bool last = (t == nt - 2);
;             const char* a1 = cA + (size_t)(t + 1) * kstep;
;             const char* a2 = last ? nA : cA + (size_t)(t + 2) * kstep; const char* b2 = last ? nB : cB + (size_t)(t + 2) * kstep;
;             const char* a3 = a2 + kstep; const char* b3 = b2 + kstep;
;             if (last && has_next) S.a_ready(nxt);
;             PG8_LDB(B0, 0, 0); PG8_LDB(B1, 0, 1); PG8_SCHED; PG8_LDA(At, 0, 0); PG8_STAGE(PG8_SA(1, 1), a1 + hstep, voffA);
;             PG8_WAIT_V(8); PG8_WAIT_L(0); PG8_BAR; PG8_MMA(0, 0, At, B0); PG8_MMA(0, 1, At, B1); PG8_BAR; PG8_SCHED;
;             PG8_LDA(At, 0, 1); PG8_STAGE(PG8_SB(0, 0), b2, voffB); PG8_STAGE(PG8_SB(0, 1), b2 + hstep, voffB); PG8_STAGE(PG8_SA(0, 0), a2, voffA);
.LBB0_582:
	s_add_u32 s24, s22, 0xfffe0080
	s_addc_u32 s25, s23, -1
	s_add_i32 s50, 0, 0x10000
	s_cmp_eq_u32 s49, 4
	s_cselect_b32 s27, s15, s25
	s_cselect_b32 s26, s45, s24
	v_add_u32_e32 v141, s50, v139
	s_cselect_b32 s25, s9, s48
	s_cselect_b32 s24, s46, s47
	s_add_i32 s52, 0, 0x14000
	ds_read_b128 v[142:145], v141
	ds_read_b128 v[146:149], v141 offset:1024
	ds_read_b128 v[150:153], v141 offset:2048
	ds_read_b128 v[154:157], v141 offset:3072
	v_add_u32_e32 v141, s52, v139
	ds_read_b128 v[158:161], v141
	ds_read_b128 v[162:165], v141 offset:1024
	ds_read_b128 v[166:169], v141 offset:2048
	ds_read_b128 v[170:173], v141 offset:3072
	v_lshl_add_u64 v[194:195], s[22:23], 0, v[136:137]
	s_add_i32 m0, s21, 0xc000
	ds_read_b128 v[174:177], v140
	ds_read_b128 v[178:181], v140 offset:1024
	ds_read_b128 v[182:185], v140 offset:2048
	ds_read_b128 v[186:189], v140 offset:3072
	ds_read_b128 v[190:193], v140 offset:4096
	ds_read_b128 v[208:211], v140 offset:5120
	ds_read_b128 v[212:215], v140 offset:6144
	ds_read_b128 v[216:219], v140 offset:7168
	global_load_lds_dwordx4 v[194:195], off
	v_lshl_add_u64 v[194:195], s[22:23], 0, v[134:135]
	s_add_i32 m0, s21, 0xe000
	s_nop 0
	global_load_lds_dwordx4 v[194:195], off
	s_waitcnt vmcnt(8)
	s_waitcnt lgkmcnt(0)
	s_barrier
	s_waitcnt lgkmcnt(0)
	v_mfma_f32_16x16x32_f16 v[128:131], v[142:145], v[174:177], v[128:131]
	v_mfma_f32_16x16x32_f16 v[120:123], v[150:153], v[174:177], v[120:123]
	v_mfma_f32_16x16x32_f16 v[112:115], v[142:145], v[182:185], v[112:115]
	v_mfma_f32_16x16x32_f16 v[104:107], v[150:153], v[182:185], v[104:107]
	v_mfma_f32_16x16x32_f16 v[96:99], v[142:145], v[190:193], v[96:99]
	v_mfma_f32_16x16x32_f16 v[88:91], v[150:153], v[190:193], v[88:91]
	v_mfma_f32_16x16x32_f16 v[80:83], v[142:145], v[212:215], v[80:83]
	v_mfma_f32_16x16x32_f16 v[72:75], v[150:153], v[212:215], v[72:75]
	v_mfma_f32_16x16x32_f16 v[128:131], v[146:149], v[178:181], v[128:131]
	v_mfma_f32_16x16x32_f16 v[120:123], v[154:157], v[178:181], v[120:123]
	v_mfma_f32_16x16x32_f16 v[112:115], v[146:149], v[186:189], v[112:115]
	v_mfma_f32_16x16x32_f16 v[104:107], v[154:157], v[186:189], v[104:107]
	v_mfma_f32_16x16x32_f16 v[96:99], v[146:149], v[208:211], v[96:99]
	v_mfma_f32_16x16x32_f16 v[88:91], v[154:157], v[208:211], v[88:91]
	v_mfma_f32_16x16x32_f16 v[80:83], v[146:149], v[216:219], v[80:83]
	v_mfma_f32_16x16x32_f16 v[72:75], v[154:157], v[216:219], v[72:75]
	v_mfma_f32_16x16x32_f16 v[124:127], v[158:161], v[174:177], v[124:127]
	v_mfma_f32_16x16x32_f16 v[116:119], v[166:169], v[174:177], v[116:119]
	v_mfma_f32_16x16x32_f16 v[108:111], v[158:161], v[182:185], v[108:111]
	v_mfma_f32_16x16x32_f16 v[100:103], v[166:169], v[182:185], v[100:103]
	v_mfma_f32_16x16x32_f16 v[92:95], v[158:161], v[190:193], v[92:95]
	v_mfma_f32_16x16x32_f16 v[84:87], v[166:169], v[190:193], v[84:87]
	v_mfma_f32_16x16x32_f16 v[76:79], v[158:161], v[212:215], v[76:79]
	v_mfma_f32_16x16x32_f16 v[68:71], v[166:169], v[212:215], v[68:71]
	v_mfma_f32_16x16x32_f16 v[124:127], v[162:165], v[178:181], v[124:127]
	v_mfma_f32_16x16x32_f16 v[116:119], v[170:173], v[178:181], v[116:119]
	v_mfma_f32_16x16x32_f16 v[108:111], v[162:165], v[186:189], v[108:111]
	v_mfma_f32_16x16x32_f16 v[100:103], v[170:173], v[186:189], v[100:103]
	v_mfma_f32_16x16x32_f16 v[92:95], v[162:165], v[208:211], v[92:95]
	v_mfma_f32_16x16x32_f16 v[84:87], v[170:173], v[208:211], v[84:87]
	v_mfma_f32_16x16x32_f16 v[76:79], v[162:165], v[216:219], v[76:79]
	v_mfma_f32_16x16x32_f16 v[68:71], v[170:173], v[216:219], v[68:71]
	s_barrier
	s_add_i32 s50, s50, s36
	v_lshl_add_u64 v[194:195], s[24:25], 0, v[0:1]
	s_mov_b32 m0, s50
	ds_read_b128 v[174:177], v140 offset:16384
	ds_read_b128 v[178:181], v140 offset:17408
	ds_read_b128 v[182:185], v140 offset:18432
	ds_read_b128 v[186:189], v140 offset:19456
	ds_read_b128 v[190:193], v140 offset:20480
	ds_read_b128 v[208:211], v140 offset:21504
	ds_read_b128 v[212:215], v140 offset:22528
	ds_read_b128 v[216:219], v140 offset:23552
	global_load_lds_dwordx4 v[194:195], off
	s_add_i32 m0, s50, 0x2000
	s_add_u32 s50, s24, 0x20000
	v_lshl_add_u64 v[220:221], s[24:25], 0, v[132:133]
	s_addc_u32 s51, s25, 0
	s_add_i32 s52, s52, s36
	global_load_lds_dwordx4 v[220:221], off
	v_lshl_add_u64 v[222:223], s[50:51], 0, v[0:1]
	s_mov_b32 m0, s52
	v_lshl_add_u64 v[224:225], s[26:27], 0, v[132:133]
	global_load_lds_dwordx4 v[222:223], off
	v_lshl_add_u64 v[222:223], s[50:51], 0, v[132:133]
	s_add_i32 m0, s52, 0x2000
	s_nop 0
	global_load_lds_dwordx4 v[222:223], off
	v_lshl_add_u64 v[222:223], s[26:27], 0, v[0:1]
	s_mov_b32 m0, s21
	s_nop 0
	global_load_lds_dwordx4 v[222:223], off
	s_mov_b32 m0, s37
	s_nop 0
	global_load_lds_dwordx4 v[224:225], off
	s_waitcnt vmcnt(8)
	s_waitcnt lgkmcnt(0)
	s_barrier
; #define PG8_STAGE(bufoff, gbase, voff) do { _Pragma("unroll") for (int _i = 0; _i < 2; ++_i) \
;         __builtin_amdgcn_global_load_lds((const unsigned*)((const char*)(gbase) + (voff)[_i]), (LAS unsigned*)(lds + (bufoff) + ldsw + _i * 8192), 16, 0, 0); } while (0)
; #define PG8_LDA(dst, b, h) do { _Pragma("unroll") for (int m = 0; m < 4; ++m) _Pragma("unroll") for (int k = 0; k < 2; ++k) dst[m][k] = *(const LAS bf16x8*)(lds + PG8_SA(b, h) + aoff + m * 2048 + k * 1024); } while (0)
; #define PG8_LDB(dst, b, h) do { _Pragma("unroll") for (int n = 0; n < 2; ++n) _Pragma("unroll") for (int k = 0; k < 2; ++k) dst[n][k] = *(const LAS bf16x8*)(lds + PG8_SB(b, h) + boff + n * 2048 + k * 1024); } while (0)
; #define PG8_WAIT_V(n) asm volatile("s_waitcnt vmcnt(" #n ")" ::: "memory")
; #define PG8_WAIT_L(n) asm volatile("s_waitcnt lgkmcnt(" #n ")" ::: "memory")
; #define PG8_BAR __builtin_amdgcn_s_barrier()
; #define PG8_SCHED __builtin_amdgcn_sched_barrier(0)
; template <class Epi, class Sched, bool FUSED = false, bool APERM = false>
; __device__ __forceinline__ void gemm_phase(int wid_s, LAS unsigned char* lds, const Gemm g, const Sched& S, const Epi& E) {
;     ...
;             PG8_WAIT_V(8); PG8_WAIT_L(0); PG8_BAR; PG8_MMA(1, 0, At, B0); PG8_MMA(1, 1, At, B1); PG8_BAR; PG8_SCHED;
;             PG8_LDB(B0, 1, 0); PG8_LDB(B1, 1, 1); PG8_SCHED; PG8_LDA(At, 1, 0); PG8_STAGE(PG8_SA(0, 1), a2 + hstep, voffA);
;             PG8_WAIT_V(8); PG8_WAIT_L(0); PG8_BAR; PG8_MMA(0, 0, At, B0); PG8_MMA(0, 1, At, B1); PG8_BAR; PG8_SCHED;
	s_waitcnt lgkmcnt(0)
	v_mfma_f32_16x16x32_f16 v[64:67], v[142:145], v[174:177], v[64:67]
	v_mfma_f32_16x16x32_f16 v[56:59], v[150:153], v[174:177], v[56:59]
	v_mfma_f32_16x16x32_f16 v[48:51], v[142:145], v[182:185], v[48:51]
	v_mfma_f32_16x16x32_f16 v[40:43], v[150:153], v[182:185], v[40:43]
	v_mfma_f32_16x16x32_f16 v[32:35], v[142:145], v[190:193], v[32:35]
	v_mfma_f32_16x16x32_f16 v[24:27], v[150:153], v[190:193], v[24:27]
	v_mfma_f32_16x16x32_f16 v[16:19], v[142:145], v[212:215], v[16:19]
	v_mfma_f32_16x16x32_f16 v[8:11], v[150:153], v[212:215], v[8:11]
	v_mfma_f32_16x16x32_f16 v[64:67], v[146:149], v[178:181], v[64:67]
	v_mfma_f32_16x16x32_f16 v[56:59], v[154:157], v[178:181], v[56:59]
	v_mfma_f32_16x16x32_f16 v[48:51], v[146:149], v[186:189], v[48:51]
	v_mfma_f32_16x16x32_f16 v[40:43], v[154:157], v[186:189], v[40:43]
	v_mfma_f32_16x16x32_f16 v[32:35], v[146:149], v[208:211], v[32:35]
	v_mfma_f32_16x16x32_f16 v[24:27], v[154:157], v[208:211], v[24:27]
	v_mfma_f32_16x16x32_f16 v[16:19], v[146:149], v[216:219], v[16:19]
	v_mfma_f32_16x16x32_f16 v[8:11], v[154:157], v[216:219], v[8:11]
	v_mfma_f32_16x16x32_f16 v[60:63], v[158:161], v[174:177], v[60:63]
	v_mfma_f32_16x16x32_f16 v[52:55], v[166:169], v[174:177], v[52:55]
	v_mfma_f32_16x16x32_f16 v[44:47], v[158:161], v[182:185], v[44:47]
	v_mfma_f32_16x16x32_f16 v[36:39], v[166:169], v[182:185], v[36:39]
	v_mfma_f32_16x16x32_f16 v[28:31], v[158:161], v[190:193], v[28:31]
	v_mfma_f32_16x16x32_f16 v[20:23], v[166:169], v[190:193], v[20:23]
	v_mfma_f32_16x16x32_f16 v[12:15], v[158:161], v[212:215], v[12:15]
	v_mfma_f32_16x16x32_f16 v[4:7], v[166:169], v[212:215], v[4:7]
	v_mfma_f32_16x16x32_f16 v[60:63], v[162:165], v[178:181], v[60:63]
	v_mfma_f32_16x16x32_f16 v[52:55], v[170:173], v[178:181], v[52:55]
	v_mfma_f32_16x16x32_f16 v[44:47], v[162:165], v[186:189], v[44:47]
	v_mfma_f32_16x16x32_f16 v[36:39], v[170:173], v[186:189], v[36:39]
	v_mfma_f32_16x16x32_f16 v[28:31], v[162:165], v[208:211], v[28:31]
	v_mfma_f32_16x16x32_f16 v[20:23], v[170:173], v[208:211], v[20:23]
	v_mfma_f32_16x16x32_f16 v[12:15], v[162:165], v[216:219], v[12:15]
	v_mfma_f32_16x16x32_f16 v[4:7], v[170:173], v[216:219], v[4:7]
	s_barrier
	s_add_i32 s50, 0, 0x18000
	v_add_u32_e32 v141, s50, v139
	s_add_i32 s51, 0, 0x1c000
	ds_read_b128 v[142:145], v141
	ds_read_b128 v[146:149], v141 offset:1024
	ds_read_b128 v[150:153], v141 offset:2048
	ds_read_b128 v[154:157], v141 offset:3072
	v_add_u32_e32 v141, s51, v139
	ds_read_b128 v[158:161], v141
	ds_read_b128 v[162:165], v141 offset:1024
	ds_read_b128 v[166:169], v141 offset:2048
	ds_read_b128 v[170:173], v141 offset:3072
	s_add_u32 s26, s26, 0x20000
	s_addc_u32 s27, s27, 0
	s_mov_b32 m0, s38
	v_lshl_add_u64 v[226:227], s[26:27], 0, v[0:1]
	ds_read_b128 v[174:177], v140 offset:32768
	ds_read_b128 v[178:181], v140 offset:33792
	ds_read_b128 v[182:185], v140 offset:34816
	ds_read_b128 v[186:189], v140 offset:35840
	ds_read_b128 v[190:193], v140 offset:36864
	ds_read_b128 v[208:211], v140 offset:37888
	ds_read_b128 v[212:215], v140 offset:38912
	ds_read_b128 v[216:219], v140 offset:39936
	global_load_lds_dwordx4 v[226:227], off
	v_lshl_add_u64 v[226:227], s[26:27], 0, v[132:133]
	s_mov_b32 m0, s39
	s_nop 0
	global_load_lds_dwordx4 v[226:227], off
	s_waitcnt vmcnt(8)
	s_waitcnt lgkmcnt(0)
	s_barrier
	s_waitcnt lgkmcnt(0)
	v_mfma_f32_16x16x32_f16 v[128:131], v[142:145], v[174:177], v[128:131]
	v_mfma_f32_16x16x32_f16 v[120:123], v[150:153], v[174:177], v[120:123]
	v_mfma_f32_16x16x32_f16 v[112:115], v[142:145], v[182:185], v[112:115]
	v_mfma_f32_16x16x32_f16 v[104:107], v[150:153], v[182:185], v[104:107]
	v_mfma_f32_16x16x32_f16 v[96:99], v[142:145], v[190:193], v[96:99]
	v_mfma_f32_16x16x32_f16 v[88:91], v[150:153], v[190:193], v[88:91]
	v_mfma_f32_16x16x32_f16 v[80:83], v[142:145], v[212:215], v[80:83]
	v_mfma_f32_16x16x32_f16 v[72:75], v[150:153], v[212:215], v[72:75]
	v_mfma_f32_16x16x32_f16 v[128:131], v[146:149], v[178:181], v[128:131]
	v_mfma_f32_16x16x32_f16 v[120:123], v[154:157], v[178:181], v[120:123]
	v_mfma_f32_16x16x32_f16 v[112:115], v[146:149], v[186:189], v[112:115]
	v_mfma_f32_16x16x32_f16 v[104:107], v[154:157], v[186:189], v[104:107]
	v_mfma_f32_16x16x32_f16 v[96:99], v[146:149], v[208:211], v[96:99]
	v_mfma_f32_16x16x32_f16 v[88:91], v[154:157], v[208:211], v[88:91]
	v_mfma_f32_16x16x32_f16 v[80:83], v[146:149], v[216:219], v[80:83]
	v_mfma_f32_16x16x32_f16 v[72:75], v[154:157], v[216:219], v[72:75]
	v_mfma_f32_16x16x32_f16 v[124:127], v[158:161], v[174:177], v[124:127]
	v_mfma_f32_16x16x32_f16 v[116:119], v[166:169], v[174:177], v[116:119]
	v_mfma_f32_16x16x32_f16 v[108:111], v[158:161], v[182:185], v[108:111]
	v_mfma_f32_16x16x32_f16 v[100:103], v[166:169], v[182:185], v[100:103]
	v_mfma_f32_16x16x32_f16 v[92:95], v[158:161], v[190:193], v[92:95]
	v_mfma_f32_16x16x32_f16 v[84:87], v[166:169], v[190:193], v[84:87]
	v_mfma_f32_16x16x32_f16 v[76:79], v[158:161], v[212:215], v[76:79]
	v_mfma_f32_16x16x32_f16 v[68:71], v[166:169], v[212:215], v[68:71]
	v_mfma_f32_16x16x32_f16 v[124:127], v[162:165], v[178:181], v[124:127]
	v_mfma_f32_16x16x32_f16 v[116:119], v[170:173], v[178:181], v[116:119]
	v_mfma_f32_16x16x32_f16 v[108:111], v[162:165], v[186:189], v[108:111]
	v_mfma_f32_16x16x32_f16 v[100:103], v[170:173], v[186:189], v[100:103]
	v_mfma_f32_16x16x32_f16 v[92:95], v[162:165], v[208:211], v[92:95]
	v_mfma_f32_16x16x32_f16 v[84:87], v[170:173], v[208:211], v[84:87]
	v_mfma_f32_16x16x32_f16 v[76:79], v[162:165], v[216:219], v[76:79]
	v_mfma_f32_16x16x32_f16 v[68:71], v[170:173], v[216:219], v[68:71]
	s_barrier
; #define PG8_STAGE(bufoff, gbase, voff) do { _Pragma("unroll") for (int _i = 0; _i < 2; ++_i) \
;         __builtin_amdgcn_global_load_lds((const unsigned*)((const char*)(gbase) + (voff)[_i]), (LAS unsigned*)(lds + (bufoff) + ldsw + _i * 8192), 16, 0, 0); } while (0)
; #define PG8_LDA(dst, b, h) do { _Pragma("unroll") for (int m = 0; m < 4; ++m) _Pragma("unroll") for (int k = 0; k < 2; ++k) dst[m][k] = *(const LAS bf16x8*)(lds + PG8_SA(b, h) + aoff + m * 2048 + k * 1024); } while (0)
; #define PG8_WAIT_V(n) asm volatile("s_waitcnt vmcnt(" #n ")" ::: "memory")
; #define PG8_WAIT_L(n) asm volatile("s_waitcnt lgkmcnt(" #n ")" ::: "memory")
; #define PG8_BAR __builtin_amdgcn_s_barrier()
; #define PG8_SCHED __builtin_amdgcn_sched_barrier(0)
; template <class Epi, class Sched, bool FUSED = false, bool APERM = false>
; __device__ __forceinline__ void gemm_phase(int wid_s, LAS unsigned char* lds, const Gemm g, const Sched& S, const Epi& E) {
;     ...
;             PG8_LDA(At, 1, 1); PG8_STAGE(PG8_SB(1, 0), b3, voffB); PG8_STAGE(PG8_SB(1, 1), b3 + hstep, voffB); PG8_STAGE(PG8_SA(1, 0), a3, voffA);
;             PG8_WAIT_V(8); PG8_WAIT_L(0); PG8_BAR; PG8_MMA(1, 0, At, B0); PG8_MMA(1, 1, At, B1); PG8_BAR; PG8_SCHED;
;         }
	s_add_i32 s26, s50, s36
	v_lshl_add_u64 v[194:195], v[194:195], 0, s[12:13]
	s_mov_b32 m0, s26
	ds_read_b128 v[174:177], v140 offset:49152
	ds_read_b128 v[178:181], v140 offset:50176
	ds_read_b128 v[182:185], v140 offset:51200
	ds_read_b128 v[186:189], v140 offset:52224
	ds_read_b128 v[190:193], v140 offset:53248
	ds_read_b128 v[208:211], v140 offset:54272
	ds_read_b128 v[212:215], v140 offset:55296
	ds_read_b128 v[216:219], v140 offset:56320
	global_load_lds_dwordx4 v[194:195], off
	s_add_i32 m0, s26, 0x2000
	s_add_u32 s24, s24, 0x20080
	v_lshl_add_u64 v[194:195], v[220:221], 0, s[12:13]
	s_addc_u32 s25, s25, 0
	s_add_i32 s26, s51, s36
	global_load_lds_dwordx4 v[194:195], off
	v_lshl_add_u64 v[194:195], s[24:25], 0, v[0:1]
	s_mov_b32 m0, s26
	s_nop 0
	global_load_lds_dwordx4 v[194:195], off
	v_lshl_add_u64 v[194:195], s[24:25], 0, v[132:133]
	s_add_i32 m0, s26, 0x2000
	s_nop 0
	global_load_lds_dwordx4 v[194:195], off
	v_lshl_add_u64 v[194:195], v[222:223], 0, s[12:13]
	s_mov_b32 m0, s41
	s_nop 0
	global_load_lds_dwordx4 v[194:195], off
	v_lshl_add_u64 v[194:195], v[224:225], 0, s[12:13]
	s_mov_b32 m0, s42
	s_nop 0
	global_load_lds_dwordx4 v[194:195], off
	s_waitcnt vmcnt(8)
	s_waitcnt lgkmcnt(0)
	s_barrier
	s_waitcnt lgkmcnt(0)
	v_mfma_f32_16x16x32_f16 v[64:67], v[142:145], v[174:177], v[64:67]
	v_mfma_f32_16x16x32_f16 v[56:59], v[150:153], v[174:177], v[56:59]
	v_mfma_f32_16x16x32_f16 v[48:51], v[142:145], v[182:185], v[48:51]
	v_mfma_f32_16x16x32_f16 v[40:43], v[150:153], v[182:185], v[40:43]
	v_mfma_f32_16x16x32_f16 v[32:35], v[142:145], v[190:193], v[32:35]
	v_mfma_f32_16x16x32_f16 v[24:27], v[150:153], v[190:193], v[24:27]
	v_mfma_f32_16x16x32_f16 v[16:19], v[142:145], v[212:215], v[16:19]
	v_mfma_f32_16x16x32_f16 v[8:11], v[150:153], v[212:215], v[8:11]
	v_mfma_f32_16x16x32_f16 v[64:67], v[146:149], v[178:181], v[64:67]
	v_mfma_f32_16x16x32_f16 v[56:59], v[154:157], v[178:181], v[56:59]
	v_mfma_f32_16x16x32_f16 v[48:51], v[146:149], v[186:189], v[48:51]
	v_mfma_f32_16x16x32_f16 v[40:43], v[154:157], v[186:189], v[40:43]
	v_mfma_f32_16x16x32_f16 v[32:35], v[146:149], v[208:211], v[32:35]
	v_mfma_f32_16x16x32_f16 v[24:27], v[154:157], v[208:211], v[24:27]
	v_mfma_f32_16x16x32_f16 v[16:19], v[146:149], v[216:219], v[16:19]
	v_mfma_f32_16x16x32_f16 v[8:11], v[154:157], v[216:219], v[8:11]
	v_mfma_f32_16x16x32_f16 v[60:63], v[158:161], v[174:177], v[60:63]
	v_mfma_f32_16x16x32_f16 v[52:55], v[166:169], v[174:177], v[52:55]
	v_mfma_f32_16x16x32_f16 v[44:47], v[158:161], v[182:185], v[44:47]
	v_mfma_f32_16x16x32_f16 v[36:39], v[166:169], v[182:185], v[36:39]
	v_mfma_f32_16x16x32_f16 v[28:31], v[158:161], v[190:193], v[28:31]
	v_mfma_f32_16x16x32_f16 v[20:23], v[166:169], v[190:193], v[20:23]
	v_mfma_f32_16x16x32_f16 v[12:15], v[158:161], v[212:215], v[12:15]
	v_mfma_f32_16x16x32_f16 v[4:7], v[166:169], v[212:215], v[4:7]
	v_mfma_f32_16x16x32_f16 v[60:63], v[162:165], v[178:181], v[60:63]
	v_mfma_f32_16x16x32_f16 v[52:55], v[170:173], v[178:181], v[52:55]
	v_mfma_f32_16x16x32_f16 v[44:47], v[162:165], v[186:189], v[44:47]
	v_mfma_f32_16x16x32_f16 v[36:39], v[170:173], v[186:189], v[36:39]
	v_mfma_f32_16x16x32_f16 v[28:31], v[162:165], v[208:211], v[28:31]
	v_mfma_f32_16x16x32_f16 v[20:23], v[170:173], v[208:211], v[20:23]
	v_mfma_f32_16x16x32_f16 v[12:15], v[162:165], v[216:219], v[12:15]
	v_mfma_f32_16x16x32_f16 v[4:7], v[170:173], v[216:219], v[4:7]
	s_barrier
	s_add_i32 s49, s49, 2
	s_add_u32 s47, s47, 0x100
	s_addc_u32 s48, s48, 0
	s_add_u32 s22, s22, 0x100
	s_addc_u32 s23, s23, 0
	s_cmp_gt_u32 s49, 5
	s_cbranch_scc0 .LBB0_582
	s_and_b64 vcc, exec, s[6:7]
	s_cbranch_vccz .LBB0_585
	s_barrier

; #define PG8_STAGE(bufoff, gbase, voff) do { _Pragma("unroll") for (int _i = 0; _i < 2; ++_i) \
;         __builtin_amdgcn_global_load_lds((const unsigned*)((const char*)(gbase) + (voff)[_i]), (LAS unsigned*)(lds + (bufoff) + ldsw + _i * 8192), 16, 0, 0); } while (0)
; #define PG8_LDA(dst, b, h) do { _Pragma("unroll") for (int m = 0; m < 4; ++m) _Pragma("unroll") for (int k = 0; k < 2; ++k) dst[m][k] = *(const LAS bf16x8*)(lds + PG8_SA(b, h) + aoff + m * 2048 + k * 1024); } while (0)
; #define PG8_LDB(dst, b, h) do { _Pragma("unroll") for (int n = 0; n < 2; ++n) _Pragma("unroll") for (int k = 0; k < 2; ++k) dst[n][k] = *(const LAS bf16x8*)(lds + PG8_SB(b, h) + boff + n * 2048 + k * 1024); } while (0)
; #define PG8_WAIT_V(n) asm volatile("s_waitcnt vmcnt(" #n ")" ::: "memory")
; #define PG8_WAIT_L(n) asm volatile("s_waitcnt lgkmcnt(" #n ")" ::: "memory")
; #define PG8_BAR __builtin_amdgcn_s_barrier()
; #define PG8_SCHED __builtin_amdgcn_sched_barrier(0)
; template <class Epi, class Sched, bool FUSED = false, bool APERM = false>
; __device__ __forceinline__ void gemm_phase(int wid_s, LAS unsigned char* lds, const Gemm g, const Sched& S, const Epi& E) {
;     ...
;             const bool last = (t == nt - 2);
;             const char* a1 = cA + (size_t)(t + 1) * kstep;
;             const char* a2 = last ? nA : cA + (size_t)(t + 2) * kstep; const char* b2 = last ? nB : cB + (size_t)(t + 2) * kstep;
;             const char* a3 = a2 + kstep; const char* b3 = b2 + kstep;
;             if (last && has_next) S.a_ready(nxt);
;             PG8_LDB(B0, 0, 0); PG8_LDB(B1, 0, 1); PG8_SCHED; PG8_LDA(At, 0, 0); PG8_STAGE(PG8_SA(1, 1), a1 + hstep, voffA);
;             PG8_WAIT_V(8); PG8_WAIT_L(0); PG8_BAR; PG8_MMA(0, 0, At, B0); PG8_MMA(0, 1, At, B1); PG8_BAR; PG8_SCHED;
;             PG8_LDA(At, 0, 1); PG8_STAGE(PG8_SB(0, 0), b2, voffB); PG8_STAGE(PG8_SB(0, 1), b2 + hstep, voffB); PG8_STAGE(PG8_SA(0, 0), a2, voffA);
.LBB0_653:
	s_add_u32 s38, s28, s36
	s_addc_u32 s39, s29, s37
	s_add_u32 s38, s38, 0x100
	s_addc_u32 s39, s39, 0
	s_add_u32 s63, s58, s36
	s_addc_u32 s64, s59, s37
	s_add_i32 s65, 0, 0x10000
	s_cmpk_eq_i32 s36, 0xf00
	s_cselect_b32 s41, s27, s39
	s_cselect_b32 s40, s60, s38
	v_add_u32_e32 v143, s65, v3
	s_cselect_b32 s39, s25, s64
	s_cselect_b32 s38, s61, s63
	s_add_i32 s63, 0, 0x14000
	ds_read_b128 v[144:147], v143
	ds_read_b128 v[148:151], v143 offset:1024
	ds_read_b128 v[152:155], v143 offset:2048
	ds_read_b128 v[156:159], v143 offset:3072
	v_add_u32_e32 v143, s63, v3
	ds_read_b128 v[160:163], v143
	ds_read_b128 v[164:167], v143 offset:1024
	ds_read_b128 v[168:171], v143 offset:2048
	ds_read_b128 v[172:175], v143 offset:3072
	v_lshl_add_u64 v[222:223], v[140:141], 0, s[36:37]
	s_add_i32 m0, s15, 0xc000
	ds_read_b128 v[176:179], v142
	ds_read_b128 v[180:183], v142 offset:1024
	ds_read_b128 v[184:187], v142 offset:2048
	ds_read_b128 v[188:191], v142 offset:3072
	ds_read_b128 v[192:195], v142 offset:4096
	ds_read_b128 v[208:211], v142 offset:5120
	ds_read_b128 v[212:215], v142 offset:6144
	ds_read_b128 v[216:219], v142 offset:7168
	global_load_lds_dwordx4 v[222:223], off
	v_lshl_add_u64 v[222:223], v[138:139], 0, s[36:37]
	s_add_i32 m0, s15, 0xe000
	s_nop 0
	global_load_lds_dwordx4 v[222:223], off
	s_waitcnt vmcnt(8)
	s_waitcnt lgkmcnt(0)
	s_barrier
	s_waitcnt lgkmcnt(0)
	v_mfma_f32_16x16x32_f16 v[128:131], v[144:147], v[176:179], v[128:131]
	v_mfma_f32_16x16x32_f16 v[124:127], v[152:155], v[176:179], v[124:127]
	v_mfma_f32_16x16x32_f16 v[112:115], v[144:147], v[184:187], v[112:115]
	v_mfma_f32_16x16x32_f16 v[108:111], v[152:155], v[184:187], v[108:111]
	v_mfma_f32_16x16x32_f16 v[96:99], v[144:147], v[192:195], v[96:99]
	v_mfma_f32_16x16x32_f16 v[92:95], v[152:155], v[192:195], v[92:95]
	v_mfma_f32_16x16x32_f16 v[80:83], v[144:147], v[212:215], v[80:83]
	v_mfma_f32_16x16x32_f16 v[76:79], v[152:155], v[212:215], v[76:79]
	v_mfma_f32_16x16x32_f16 v[128:131], v[148:151], v[180:183], v[128:131]
	v_mfma_f32_16x16x32_f16 v[124:127], v[156:159], v[180:183], v[124:127]
	v_mfma_f32_16x16x32_f16 v[112:115], v[148:151], v[188:191], v[112:115]
	v_mfma_f32_16x16x32_f16 v[108:111], v[156:159], v[188:191], v[108:111]
	v_mfma_f32_16x16x32_f16 v[96:99], v[148:151], v[208:211], v[96:99]
	v_mfma_f32_16x16x32_f16 v[92:95], v[156:159], v[208:211], v[92:95]
	v_mfma_f32_16x16x32_f16 v[80:83], v[148:151], v[216:219], v[80:83]
	v_mfma_f32_16x16x32_f16 v[76:79], v[156:159], v[216:219], v[76:79]
	v_mfma_f32_16x16x32_f16 v[120:123], v[160:163], v[176:179], v[120:123]
	v_mfma_f32_16x16x32_f16 v[116:119], v[168:171], v[176:179], v[116:119]
	v_mfma_f32_16x16x32_f16 v[104:107], v[160:163], v[184:187], v[104:107]
	v_mfma_f32_16x16x32_f16 v[100:103], v[168:171], v[184:187], v[100:103]
	v_mfma_f32_16x16x32_f16 v[88:91], v[160:163], v[192:195], v[88:91]
	v_mfma_f32_16x16x32_f16 v[84:87], v[168:171], v[192:195], v[84:87]
	v_mfma_f32_16x16x32_f16 v[72:75], v[160:163], v[212:215], v[72:75]
	v_mfma_f32_16x16x32_f16 v[68:71], v[168:171], v[212:215], v[68:71]
	v_mfma_f32_16x16x32_f16 v[120:123], v[164:167], v[180:183], v[120:123]
	v_mfma_f32_16x16x32_f16 v[116:119], v[172:175], v[180:183], v[116:119]
	v_mfma_f32_16x16x32_f16 v[104:107], v[164:167], v[188:191], v[104:107]
	v_mfma_f32_16x16x32_f16 v[100:103], v[172:175], v[188:191], v[100:103]
	v_mfma_f32_16x16x32_f16 v[88:91], v[164:167], v[208:211], v[88:91]
	v_mfma_f32_16x16x32_f16 v[84:87], v[172:175], v[208:211], v[84:87]
	v_mfma_f32_16x16x32_f16 v[72:75], v[164:167], v[216:219], v[72:75]
	v_mfma_f32_16x16x32_f16 v[68:71], v[172:175], v[216:219], v[68:71]
	s_barrier
	s_add_i32 s64, s65, s49
	v_lshl_add_u64 v[222:223], s[38:39], 0, v[0:1]
	s_mov_b32 m0, s64
	ds_read_b128 v[176:179], v142 offset:16384
	ds_read_b128 v[180:183], v142 offset:17408
	ds_read_b128 v[184:187], v142 offset:18432
	ds_read_b128 v[188:191], v142 offset:19456
	ds_read_b128 v[192:195], v142 offset:20480
	ds_read_b128 v[208:211], v142 offset:21504
	ds_read_b128 v[212:215], v142 offset:22528
	ds_read_b128 v[216:219], v142 offset:23552
	global_load_lds_dwordx4 v[222:223], off
	s_add_i32 m0, s64, 0x2000
	s_add_u32 s64, s38, 0x80000
	v_lshl_add_u64 v[224:225], s[38:39], 0, v[132:133]
	s_addc_u32 s65, s39, 0
	s_add_i32 s63, s63, s49
	global_load_lds_dwordx4 v[224:225], off
	v_lshl_add_u64 v[226:227], s[64:65], 0, v[0:1]
	s_mov_b32 m0, s63
	v_lshl_add_u64 v[228:229], s[40:41], 0, v[132:133]
	global_load_lds_dwordx4 v[226:227], off
	v_lshl_add_u64 v[226:227], s[64:65], 0, v[132:133]
	s_add_i32 m0, s63, 0x2000
	s_nop 0
	global_load_lds_dwordx4 v[226:227], off
	v_lshl_add_u64 v[226:227], s[40:41], 0, v[0:1]
	s_mov_b32 m0, s15
	s_nop 0
	global_load_lds_dwordx4 v[226:227], off
	s_mov_b32 m0, s50
	s_nop 0
	global_load_lds_dwordx4 v[228:229], off
	s_waitcnt vmcnt(8)
	s_waitcnt lgkmcnt(0)
	s_barrier
; #define PG8_STAGE(bufoff, gbase, voff) do { _Pragma("unroll") for (int _i = 0; _i < 2; ++_i) \
;         __builtin_amdgcn_global_load_lds((const unsigned*)((const char*)(gbase) + (voff)[_i]), (LAS unsigned*)(lds + (bufoff) + ldsw + _i * 8192), 16, 0, 0); } while (0)
; #define PG8_LDA(dst, b, h) do { _Pragma("unroll") for (int m = 0; m < 4; ++m) _Pragma("unroll") for (int k = 0; k < 2; ++k) dst[m][k] = *(const LAS bf16x8*)(lds + PG8_SA(b, h) + aoff + m * 2048 + k * 1024); } while (0)
; #define PG8_LDB(dst, b, h) do { _Pragma("unroll") for (int n = 0; n < 2; ++n) _Pragma("unroll") for (int k = 0; k < 2; ++k) dst[n][k] = *(const LAS bf16x8*)(lds + PG8_SB(b, h) + boff + n * 2048 + k * 1024); } while (0)
; #define PG8_WAIT_V(n) asm volatile("s_waitcnt vmcnt(" #n ")" ::: "memory")
; #define PG8_WAIT_L(n) asm volatile("s_waitcnt lgkmcnt(" #n ")" ::: "memory")
; #define PG8_BAR __builtin_amdgcn_s_barrier()
; #define PG8_SCHED __builtin_amdgcn_sched_barrier(0)
; template <class Epi, class Sched, bool FUSED = false, bool APERM = false>
; __device__ __forceinline__ void gemm_phase(int wid_s, LAS unsigned char* lds, const Gemm g, const Sched& S, const Epi& E) {
;     ...
;             PG8_WAIT_V(8); PG8_WAIT_L(0); PG8_BAR; PG8_MMA(1, 0, At, B0); PG8_MMA(1, 1, At, B1); PG8_BAR; PG8_SCHED;
;             PG8_LDB(B0, 1, 0); PG8_LDB(B1, 1, 1); PG8_SCHED; PG8_LDA(At, 1, 0); PG8_STAGE(PG8_SA(0, 1), a2 + hstep, voffA);
;             PG8_WAIT_V(8); PG8_WAIT_L(0); PG8_BAR; PG8_MMA(0, 0, At, B0); PG8_MMA(0, 1, At, B1); PG8_BAR; PG8_SCHED;
	s_waitcnt lgkmcnt(0)
	v_mfma_f32_16x16x32_f16 v[64:67], v[144:147], v[176:179], v[64:67]
	v_mfma_f32_16x16x32_f16 v[60:63], v[152:155], v[176:179], v[60:63]
	v_mfma_f32_16x16x32_f16 v[48:51], v[144:147], v[184:187], v[48:51]
	v_mfma_f32_16x16x32_f16 v[44:47], v[152:155], v[184:187], v[44:47]
	v_mfma_f32_16x16x32_f16 v[32:35], v[144:147], v[192:195], v[32:35]
	v_mfma_f32_16x16x32_f16 v[28:31], v[152:155], v[192:195], v[28:31]
	v_mfma_f32_16x16x32_f16 v[16:19], v[144:147], v[212:215], v[16:19]
	v_mfma_f32_16x16x32_f16 v[12:15], v[152:155], v[212:215], v[12:15]
	v_mfma_f32_16x16x32_f16 v[64:67], v[148:151], v[180:183], v[64:67]
	v_mfma_f32_16x16x32_f16 v[60:63], v[156:159], v[180:183], v[60:63]
	v_mfma_f32_16x16x32_f16 v[48:51], v[148:151], v[188:191], v[48:51]
	v_mfma_f32_16x16x32_f16 v[44:47], v[156:159], v[188:191], v[44:47]
	v_mfma_f32_16x16x32_f16 v[32:35], v[148:151], v[208:211], v[32:35]
	v_mfma_f32_16x16x32_f16 v[28:31], v[156:159], v[208:211], v[28:31]
	v_mfma_f32_16x16x32_f16 v[16:19], v[148:151], v[216:219], v[16:19]
	v_mfma_f32_16x16x32_f16 v[12:15], v[156:159], v[216:219], v[12:15]
	v_mfma_f32_16x16x32_f16 v[56:59], v[160:163], v[176:179], v[56:59]
	v_mfma_f32_16x16x32_f16 v[52:55], v[168:171], v[176:179], v[52:55]
	v_mfma_f32_16x16x32_f16 v[40:43], v[160:163], v[184:187], v[40:43]
	v_mfma_f32_16x16x32_f16 v[36:39], v[168:171], v[184:187], v[36:39]
	v_mfma_f32_16x16x32_f16 v[24:27], v[160:163], v[192:195], v[24:27]
	v_mfma_f32_16x16x32_f16 v[20:23], v[168:171], v[192:195], v[20:23]
	v_mfma_f32_16x16x32_f16 v[8:11], v[160:163], v[212:215], v[8:11]
	v_mfma_f32_16x16x32_f16 v[4:7], v[168:171], v[212:215], v[4:7]
	v_mfma_f32_16x16x32_f16 v[56:59], v[164:167], v[180:183], v[56:59]
	v_mfma_f32_16x16x32_f16 v[52:55], v[172:175], v[180:183], v[52:55]
	v_mfma_f32_16x16x32_f16 v[40:43], v[164:167], v[188:191], v[40:43]
	v_mfma_f32_16x16x32_f16 v[36:39], v[172:175], v[188:191], v[36:39]
	v_mfma_f32_16x16x32_f16 v[24:27], v[164:167], v[208:211], v[24:27]
	v_mfma_f32_16x16x32_f16 v[20:23], v[172:175], v[208:211], v[20:23]
	v_mfma_f32_16x16x32_f16 v[8:11], v[164:167], v[216:219], v[8:11]
	v_mfma_f32_16x16x32_f16 v[4:7], v[172:175], v[216:219], v[4:7]
	s_barrier
	s_add_i32 s63, 0, 0x18000
	v_add_u32_e32 v143, s63, v3
	s_add_i32 s64, 0, 0x1c000
	ds_read_b128 v[144:147], v143
	ds_read_b128 v[148:151], v143 offset:1024
	ds_read_b128 v[152:155], v143 offset:2048
	ds_read_b128 v[156:159], v143 offset:3072
	v_add_u32_e32 v143, s64, v3
	ds_read_b128 v[160:163], v143
	ds_read_b128 v[164:167], v143 offset:1024
	ds_read_b128 v[168:171], v143 offset:2048
	ds_read_b128 v[172:175], v143 offset:3072
	s_add_u32 s40, s40, 0x80000
	s_addc_u32 s41, s41, 0
	s_mov_b32 m0, s51
	v_lshl_add_u64 v[230:231], s[40:41], 0, v[0:1]
	ds_read_b128 v[176:179], v142 offset:32768
	ds_read_b128 v[180:183], v142 offset:33792
	ds_read_b128 v[184:187], v142 offset:34816
	ds_read_b128 v[188:191], v142 offset:35840
	ds_read_b128 v[192:195], v142 offset:36864
	ds_read_b128 v[208:211], v142 offset:37888
	ds_read_b128 v[212:215], v142 offset:38912
	ds_read_b128 v[216:219], v142 offset:39936
	global_load_lds_dwordx4 v[230:231], off
	v_lshl_add_u64 v[230:231], s[40:41], 0, v[132:133]
	s_mov_b32 m0, s52
	s_nop 0
	global_load_lds_dwordx4 v[230:231], off
	s_waitcnt vmcnt(8)
	s_waitcnt lgkmcnt(0)
	s_barrier
	s_waitcnt lgkmcnt(0)
	v_mfma_f32_16x16x32_f16 v[128:131], v[144:147], v[176:179], v[128:131]
	v_mfma_f32_16x16x32_f16 v[124:127], v[152:155], v[176:179], v[124:127]
	v_mfma_f32_16x16x32_f16 v[112:115], v[144:147], v[184:187], v[112:115]
	v_mfma_f32_16x16x32_f16 v[108:111], v[152:155], v[184:187], v[108:111]
	v_mfma_f32_16x16x32_f16 v[96:99], v[144:147], v[192:195], v[96:99]
	v_mfma_f32_16x16x32_f16 v[92:95], v[152:155], v[192:195], v[92:95]
	v_mfma_f32_16x16x32_f16 v[80:83], v[144:147], v[212:215], v[80:83]
	v_mfma_f32_16x16x32_f16 v[76:79], v[152:155], v[212:215], v[76:79]
	v_mfma_f32_16x16x32_f16 v[128:131], v[148:151], v[180:183], v[128:131]
	v_mfma_f32_16x16x32_f16 v[124:127], v[156:159], v[180:183], v[124:127]
	v_mfma_f32_16x16x32_f16 v[112:115], v[148:151], v[188:191], v[112:115]
	v_mfma_f32_16x16x32_f16 v[108:111], v[156:159], v[188:191], v[108:111]
	v_mfma_f32_16x16x32_f16 v[96:99], v[148:151], v[208:211], v[96:99]
	v_mfma_f32_16x16x32_f16 v[92:95], v[156:159], v[208:211], v[92:95]
	v_mfma_f32_16x16x32_f16 v[80:83], v[148:151], v[216:219], v[80:83]
	v_mfma_f32_16x16x32_f16 v[76:79], v[156:159], v[216:219], v[76:79]
	v_mfma_f32_16x16x32_f16 v[120:123], v[160:163], v[176:179], v[120:123]
	v_mfma_f32_16x16x32_f16 v[116:119], v[168:171], v[176:179], v[116:119]
	v_mfma_f32_16x16x32_f16 v[104:107], v[160:163], v[184:187], v[104:107]
	v_mfma_f32_16x16x32_f16 v[100:103], v[168:171], v[184:187], v[100:103]
	v_mfma_f32_16x16x32_f16 v[88:91], v[160:163], v[192:195], v[88:91]
	v_mfma_f32_16x16x32_f16 v[84:87], v[168:171], v[192:195], v[84:87]
	v_mfma_f32_16x16x32_f16 v[72:75], v[160:163], v[212:215], v[72:75]
	v_mfma_f32_16x16x32_f16 v[68:71], v[168:171], v[212:215], v[68:71]
	v_mfma_f32_16x16x32_f16 v[120:123], v[164:167], v[180:183], v[120:123]
	v_mfma_f32_16x16x32_f16 v[116:119], v[172:175], v[180:183], v[116:119]
	v_mfma_f32_16x16x32_f16 v[104:107], v[164:167], v[188:191], v[104:107]
	v_mfma_f32_16x16x32_f16 v[100:103], v[172:175], v[188:191], v[100:103]
	v_mfma_f32_16x16x32_f16 v[88:91], v[164:167], v[208:211], v[88:91]
	v_mfma_f32_16x16x32_f16 v[84:87], v[172:175], v[208:211], v[84:87]
	v_mfma_f32_16x16x32_f16 v[72:75], v[164:167], v[216:219], v[72:75]
	v_mfma_f32_16x16x32_f16 v[68:71], v[172:175], v[216:219], v[68:71]
	s_barrier
; #define PG8_STAGE(bufoff, gbase, voff) do { _Pragma("unroll") for (int _i = 0; _i < 2; ++_i) \
;         __builtin_amdgcn_global_load_lds((const unsigned*)((const char*)(gbase) + (voff)[_i]), (LAS unsigned*)(lds + (bufoff) + ldsw + _i * 8192), 16, 0, 0); } while (0)
; #define PG8_LDA(dst, b, h) do { _Pragma("unroll") for (int m = 0; m < 4; ++m) _Pragma("unroll") for (int k = 0; k < 2; ++k) dst[m][k] = *(const LAS bf16x8*)(lds + PG8_SA(b, h) + aoff + m * 2048 + k * 1024); } while (0)
; #define PG8_WAIT_V(n) asm volatile("s_waitcnt vmcnt(" #n ")" ::: "memory")
; #define PG8_WAIT_L(n) asm volatile("s_waitcnt lgkmcnt(" #n ")" ::: "memory")
; #define PG8_BAR __builtin_amdgcn_s_barrier()
; #define PG8_SCHED __builtin_amdgcn_sched_barrier(0)
; template <class Epi, class Sched, bool FUSED = false, bool APERM = false>
; __device__ __forceinline__ void gemm_phase(int wid_s, LAS unsigned char* lds, const Gemm g, const Sched& S, const Epi& E) {
;     ...
;             PG8_LDA(At, 1, 1); PG8_STAGE(PG8_SB(1, 0), b3, voffB); PG8_STAGE(PG8_SB(1, 1), b3 + hstep, voffB); PG8_STAGE(PG8_SA(1, 0), a3, voffA);
;             PG8_WAIT_V(8); PG8_WAIT_L(0); PG8_BAR; PG8_MMA(1, 0, At, B0); PG8_MMA(1, 1, At, B1); PG8_BAR; PG8_SCHED;
;         }
;         if (wr == 0) PG8_BAR;
	s_add_i32 s40, s63, s49
	v_lshl_add_u64 v[222:223], v[222:223], 0, s[12:13]
	s_mov_b32 m0, s40
	ds_read_b128 v[176:179], v142 offset:49152
	ds_read_b128 v[180:183], v142 offset:50176
	ds_read_b128 v[184:187], v142 offset:51200
	ds_read_b128 v[188:191], v142 offset:52224
	ds_read_b128 v[192:195], v142 offset:53248
	ds_read_b128 v[208:211], v142 offset:54272
	ds_read_b128 v[212:215], v142 offset:55296
	ds_read_b128 v[216:219], v142 offset:56320
	global_load_lds_dwordx4 v[222:223], off
	s_add_i32 m0, s40, 0x2000
	s_add_u32 s38, s38, 0x80080
	v_lshl_add_u64 v[222:223], v[224:225], 0, s[12:13]
	s_addc_u32 s39, s39, 0
	s_add_i32 s40, s64, s49
	global_load_lds_dwordx4 v[222:223], off
	v_lshl_add_u64 v[222:223], s[38:39], 0, v[0:1]
	s_mov_b32 m0, s40
	s_nop 0
	global_load_lds_dwordx4 v[222:223], off
	v_lshl_add_u64 v[222:223], s[38:39], 0, v[132:133]
	s_add_i32 m0, s40, 0x2000
	s_nop 0
	global_load_lds_dwordx4 v[222:223], off
	v_lshl_add_u64 v[222:223], v[226:227], 0, s[12:13]
	s_mov_b32 m0, s54
	s_nop 0
	global_load_lds_dwordx4 v[222:223], off
	v_lshl_add_u64 v[222:223], v[228:229], 0, s[12:13]
	s_mov_b32 m0, s55
	s_nop 0
	global_load_lds_dwordx4 v[222:223], off
	s_waitcnt vmcnt(8)
	s_waitcnt lgkmcnt(0)
	s_barrier
	s_waitcnt lgkmcnt(0)
	v_mfma_f32_16x16x32_f16 v[64:67], v[144:147], v[176:179], v[64:67]
	v_mfma_f32_16x16x32_f16 v[60:63], v[152:155], v[176:179], v[60:63]
	v_mfma_f32_16x16x32_f16 v[48:51], v[144:147], v[184:187], v[48:51]
	v_mfma_f32_16x16x32_f16 v[44:47], v[152:155], v[184:187], v[44:47]
	v_mfma_f32_16x16x32_f16 v[32:35], v[144:147], v[192:195], v[32:35]
	v_mfma_f32_16x16x32_f16 v[28:31], v[152:155], v[192:195], v[28:31]
	v_mfma_f32_16x16x32_f16 v[16:19], v[144:147], v[212:215], v[16:19]
	v_mfma_f32_16x16x32_f16 v[12:15], v[152:155], v[212:215], v[12:15]
	v_mfma_f32_16x16x32_f16 v[64:67], v[148:151], v[180:183], v[64:67]
	v_mfma_f32_16x16x32_f16 v[60:63], v[156:159], v[180:183], v[60:63]
	v_mfma_f32_16x16x32_f16 v[48:51], v[148:151], v[188:191], v[48:51]
	v_mfma_f32_16x16x32_f16 v[44:47], v[156:159], v[188:191], v[44:47]
	v_mfma_f32_16x16x32_f16 v[32:35], v[148:151], v[208:211], v[32:35]
	v_mfma_f32_16x16x32_f16 v[28:31], v[156:159], v[208:211], v[28:31]
	v_mfma_f32_16x16x32_f16 v[16:19], v[148:151], v[216:219], v[16:19]
	v_mfma_f32_16x16x32_f16 v[12:15], v[156:159], v[216:219], v[12:15]
	v_mfma_f32_16x16x32_f16 v[56:59], v[160:163], v[176:179], v[56:59]
	v_mfma_f32_16x16x32_f16 v[52:55], v[168:171], v[176:179], v[52:55]
	v_mfma_f32_16x16x32_f16 v[40:43], v[160:163], v[184:187], v[40:43]
	v_mfma_f32_16x16x32_f16 v[36:39], v[168:171], v[184:187], v[36:39]
	v_mfma_f32_16x16x32_f16 v[24:27], v[160:163], v[192:195], v[24:27]
	v_mfma_f32_16x16x32_f16 v[20:23], v[168:171], v[192:195], v[20:23]
	v_mfma_f32_16x16x32_f16 v[8:11], v[160:163], v[212:215], v[8:11]
	v_mfma_f32_16x16x32_f16 v[4:7], v[168:171], v[212:215], v[4:7]
	v_mfma_f32_16x16x32_f16 v[56:59], v[164:167], v[180:183], v[56:59]
	v_mfma_f32_16x16x32_f16 v[52:55], v[172:175], v[180:183], v[52:55]
	v_mfma_f32_16x16x32_f16 v[40:43], v[164:167], v[188:191], v[40:43]
	v_mfma_f32_16x16x32_f16 v[36:39], v[172:175], v[188:191], v[36:39]
	v_mfma_f32_16x16x32_f16 v[24:27], v[164:167], v[208:211], v[24:27]
	v_mfma_f32_16x16x32_f16 v[20:23], v[172:175], v[208:211], v[20:23]
	v_mfma_f32_16x16x32_f16 v[8:11], v[164:167], v[216:219], v[8:11]
	v_mfma_f32_16x16x32_f16 v[4:7], v[172:175], v[216:219], v[4:7]
	s_barrier
	s_add_i32 s62, s62, 2
	s_add_u32 s36, s36, 0x100
	s_addc_u32 s37, s37, 0
	s_cmp_gt_u32 s62, 29
	s_cbranch_scc0 .LBB0_653
	s_and_b64 vcc, exec, s[22:23]
	s_cbranch_vccz .LBB0_656
	s_barrier

; #define PG8_STAGE(bufoff, gbase, voff) do { _Pragma("unroll") for (int _i = 0; _i < 2; ++_i) \
;         __builtin_amdgcn_global_load_lds((const unsigned*)((const char*)(gbase) + (voff)[_i]), (LAS unsigned*)(lds + (bufoff) + ldsw + _i * 8192), 16, 0, 0); } while (0)
; #define PG8_LDA(dst, b, h) do { _Pragma("unroll") for (int m = 0; m < 4; ++m) _Pragma("unroll") for (int k = 0; k < 2; ++k) dst[m][k] = *(const LAS bf16x8*)(lds + PG8_SA(b, h) + aoff + m * 2048 + k * 1024); } while (0)
; #define PG8_LDB(dst, b, h) do { _Pragma("unroll") for (int n = 0; n < 2; ++n) _Pragma("unroll") for (int k = 0; k < 2; ++k) dst[n][k] = *(const LAS bf16x8*)(lds + PG8_SB(b, h) + boff + n * 2048 + k * 1024); } while (0)
; #define PG8_WAIT_V(n) asm volatile("s_waitcnt vmcnt(" #n ")" ::: "memory")
; #define PG8_WAIT_L(n) asm volatile("s_waitcnt lgkmcnt(" #n ")" ::: "memory")
; #define PG8_BAR __builtin_amdgcn_s_barrier()
; #define PG8_SCHED __builtin_amdgcn_sched_barrier(0)
; template <class Epi, class Sched, bool FUSED = false, bool APERM = false>
; __device__ __forceinline__ void gemm_phase(int wid_s, LAS unsigned char* lds, const Gemm g, const Sched& S, const Epi& E) {
;     ...
;             const bool last = (t == nt - 2);
;             const char* a1 = cA + (size_t)(t + 1) * kstep;
;             const char* a2 = last ? nA : cA + (size_t)(t + 2) * kstep; const char* b2 = last ? nB : cB + (size_t)(t + 2) * kstep;
;             const char* a3 = a2 + kstep; const char* b3 = b2 + kstep;
;             if (last && has_next) S.a_ready(nxt);
;             PG8_LDB(B0, 0, 0); PG8_LDB(B1, 0, 1); PG8_SCHED; PG8_LDA(At, 0, 0); PG8_STAGE(PG8_SA(1, 1), a1 + hstep, voffA);
;             PG8_WAIT_V(8); PG8_WAIT_L(0); PG8_BAR; PG8_MMA(0, 0, At, B0); PG8_MMA(0, 1, At, B1); PG8_BAR; PG8_SCHED;
;             PG8_LDA(At, 0, 1); PG8_STAGE(PG8_SB(0, 0), b2, voffB); PG8_STAGE(PG8_SB(0, 1), b2 + hstep, voffB); PG8_STAGE(PG8_SA(0, 0), a2, voffA);
.LBB0_754:
	s_add_u32 s36, s6, 0x100
	s_addc_u32 s37, s7, 0
	s_add_i32 s45, 0, 0x10000
	s_cmp_eq_u32 s44, 28
	s_cselect_b32 s41, s3, s37
	s_cselect_b32 s40, s5, s36
	s_cselect_b32 s39, s27, s43
	s_cselect_b32 s38, s29, s42
	s_add_i32 s63, 0, 0x14000
	v_add_u32_e32 v80, s45, v244
	v_add_u32_e32 v96, s63, v244
	ds_read_b128 v[68:71], v80
	ds_read_b128 v[72:75], v80 offset:1024
	ds_read_b128 v[76:79], v80 offset:2048
	ds_read_b128 v[80:83], v80 offset:3072
	ds_read_b128 v[84:87], v96
	ds_read_b128 v[88:91], v96 offset:1024
	ds_read_b128 v[92:95], v96 offset:2048
	ds_read_b128 v[96:99], v96 offset:3072
	v_lshl_add_u64 v[200:201], s[6:7], 0, v[216:217]
	s_add_i32 m0, s52, 0xc000
	ds_read_b128 v[164:167], v245
	ds_read_b128 v[168:171], v245 offset:1024
	ds_read_b128 v[172:175], v245 offset:2048
	ds_read_b128 v[176:179], v245 offset:3072
	ds_read_b128 v[180:183], v245 offset:4096
	ds_read_b128 v[184:187], v245 offset:5120
	ds_read_b128 v[188:191], v245 offset:6144
	ds_read_b128 v[192:195], v245 offset:7168
	global_load_lds_dwordx4 v[200:201], off
	v_lshl_add_u64 v[200:201], s[6:7], 0, v[214:215]
	s_add_i32 m0, s52, 0xe000
	s_nop 0
	global_load_lds_dwordx4 v[200:201], off
	s_waitcnt vmcnt(8)
	s_waitcnt lgkmcnt(0)
	s_barrier
	s_waitcnt lgkmcnt(0)
	v_mfma_f32_16x16x32_f16 v[160:163], v[68:71], v[164:167], v[160:163]
	v_mfma_f32_16x16x32_f16 v[64:67], v[76:79], v[164:167], v[64:67]
	v_mfma_f32_16x16x32_f16 v[148:151], v[68:71], v[172:175], v[148:151]
	v_mfma_f32_16x16x32_f16 v[48:51], v[76:79], v[172:175], v[48:51]
	v_mfma_f32_16x16x32_f16 v[132:135], v[68:71], v[180:183], v[132:135]
	v_mfma_f32_16x16x32_f16 v[36:39], v[76:79], v[180:183], v[36:39]
	v_mfma_f32_16x16x32_f16 v[144:147], v[68:71], v[188:191], v[144:147]
	v_mfma_f32_16x16x32_f16 v[44:47], v[76:79], v[188:191], v[44:47]
	v_mfma_f32_16x16x32_f16 v[160:163], v[72:75], v[168:171], v[160:163]
	v_mfma_f32_16x16x32_f16 v[64:67], v[80:83], v[168:171], v[64:67]
	v_mfma_f32_16x16x32_f16 v[148:151], v[72:75], v[176:179], v[148:151]
	v_mfma_f32_16x16x32_f16 v[48:51], v[80:83], v[176:179], v[48:51]
	v_mfma_f32_16x16x32_f16 v[132:135], v[72:75], v[184:187], v[132:135]
	v_mfma_f32_16x16x32_f16 v[36:39], v[80:83], v[184:187], v[36:39]
	v_mfma_f32_16x16x32_f16 v[144:147], v[72:75], v[192:195], v[144:147]
	v_mfma_f32_16x16x32_f16 v[44:47], v[80:83], v[192:195], v[44:47]
	v_mfma_f32_16x16x32_f16 v[156:159], v[84:87], v[164:167], v[156:159]
	v_mfma_f32_16x16x32_f16 v[60:63], v[92:95], v[164:167], v[60:63]
	v_mfma_f32_16x16x32_f16 v[152:155], v[84:87], v[172:175], v[152:155]
	v_mfma_f32_16x16x32_f16 v[56:59], v[92:95], v[172:175], v[56:59]
	v_mfma_f32_16x16x32_f16 v[140:143], v[84:87], v[180:183], v[140:143]
	v_mfma_f32_16x16x32_f16 v[40:43], v[92:95], v[180:183], v[40:43]
	v_mfma_f32_16x16x32_f16 v[136:139], v[84:87], v[188:191], v[136:139]
	v_mfma_f32_16x16x32_f16 v[52:55], v[92:95], v[188:191], v[52:55]
	v_mfma_f32_16x16x32_f16 v[156:159], v[88:91], v[168:171], v[156:159]
	v_mfma_f32_16x16x32_f16 v[60:63], v[96:99], v[168:171], v[60:63]
	v_mfma_f32_16x16x32_f16 v[152:155], v[88:91], v[176:179], v[152:155]
	v_mfma_f32_16x16x32_f16 v[56:59], v[96:99], v[176:179], v[56:59]
	v_mfma_f32_16x16x32_f16 v[140:143], v[88:91], v[184:187], v[140:143]
	v_mfma_f32_16x16x32_f16 v[40:43], v[96:99], v[184:187], v[40:43]
	v_mfma_f32_16x16x32_f16 v[136:139], v[88:91], v[192:195], v[136:139]
	v_mfma_f32_16x16x32_f16 v[52:55], v[96:99], v[192:195], v[52:55]
	s_barrier
	s_add_i32 s6, s45, s51
	v_lshl_add_u64 v[200:201], s[38:39], 0, v[208:209]
	s_mov_b32 m0, s6
	ds_read_b128 v[164:167], v245 offset:16384
	ds_read_b128 v[168:171], v245 offset:17408
	ds_read_b128 v[172:175], v245 offset:18432
	ds_read_b128 v[176:179], v245 offset:19456
	ds_read_b128 v[180:183], v245 offset:20480
	ds_read_b128 v[184:187], v245 offset:21504
	ds_read_b128 v[188:191], v245 offset:22528
	ds_read_b128 v[192:195], v245 offset:23552
	global_load_lds_dwordx4 v[200:201], off
	s_add_i32 m0, s6, 0x2000
	s_add_u32 s6, s38, 0x80000
	v_lshl_add_u64 v[234:235], s[38:39], 0, v[212:213]
	s_addc_u32 s7, s39, 0
	s_add_i32 s45, s63, s51
	global_load_lds_dwordx4 v[234:235], off
	v_lshl_add_u64 v[218:219], s[6:7], 0, v[208:209]
	s_mov_b32 m0, s45
	v_lshl_add_u64 v[236:237], s[40:41], 0, v[0:1]
	global_load_lds_dwordx4 v[218:219], off
	v_lshl_add_u64 v[218:219], s[6:7], 0, v[212:213]
	s_add_i32 m0, s45, 0x2000
	v_lshl_add_u64 v[238:239], s[40:41], 0, v[210:211]
	global_load_lds_dwordx4 v[218:219], off
	s_mov_b32 m0, s52
	s_nop 0
	global_load_lds_dwordx4 v[236:237], off
	s_mov_b32 m0, s53
	s_nop 0
	global_load_lds_dwordx4 v[238:239], off
	s_waitcnt vmcnt(8)
	s_waitcnt lgkmcnt(0)
	s_barrier
; #define PG8_STAGE(bufoff, gbase, voff) do { _Pragma("unroll") for (int _i = 0; _i < 2; ++_i) \
;         __builtin_amdgcn_global_load_lds((const unsigned*)((const char*)(gbase) + (voff)[_i]), (LAS unsigned*)(lds + (bufoff) + ldsw + _i * 8192), 16, 0, 0); } while (0)
; #define PG8_LDA(dst, b, h) do { _Pragma("unroll") for (int m = 0; m < 4; ++m) _Pragma("unroll") for (int k = 0; k < 2; ++k) dst[m][k] = *(const LAS bf16x8*)(lds + PG8_SA(b, h) + aoff + m * 2048 + k * 1024); } while (0)
; #define PG8_LDB(dst, b, h) do { _Pragma("unroll") for (int n = 0; n < 2; ++n) _Pragma("unroll") for (int k = 0; k < 2; ++k) dst[n][k] = *(const LAS bf16x8*)(lds + PG8_SB(b, h) + boff + n * 2048 + k * 1024); } while (0)
; #define PG8_WAIT_V(n) asm volatile("s_waitcnt vmcnt(" #n ")" ::: "memory")
; #define PG8_WAIT_L(n) asm volatile("s_waitcnt lgkmcnt(" #n ")" ::: "memory")
; #define PG8_BAR __builtin_amdgcn_s_barrier()
; #define PG8_SCHED __builtin_amdgcn_sched_barrier(0)
; template <class Epi, class Sched, bool FUSED = false, bool APERM = false>
; __device__ __forceinline__ void gemm_phase(int wid_s, LAS unsigned char* lds, const Gemm g, const Sched& S, const Epi& E) {
;     ...
;             PG8_WAIT_V(8); PG8_WAIT_L(0); PG8_BAR; PG8_MMA(1, 0, At, B0); PG8_MMA(1, 1, At, B1); PG8_BAR; PG8_SCHED;
;             PG8_LDB(B0, 1, 0); PG8_LDB(B1, 1, 1); PG8_SCHED; PG8_LDA(At, 1, 0); PG8_STAGE(PG8_SA(0, 1), a2 + hstep, voffA);
;             PG8_WAIT_V(8); PG8_WAIT_L(0); PG8_BAR; PG8_MMA(0, 0, At, B0); PG8_MMA(0, 1, At, B1); PG8_BAR; PG8_SCHED;
	s_waitcnt lgkmcnt(0)
	v_mfma_f32_16x16x32_f16 v[128:131], v[68:71], v[164:167], v[128:131]
	v_mfma_f32_16x16x32_f16 v[32:35], v[76:79], v[164:167], v[32:35]
	v_mfma_f32_16x16x32_f16 v[120:123], v[68:71], v[172:175], v[120:123]
	v_mfma_f32_16x16x32_f16 v[24:27], v[76:79], v[172:175], v[24:27]
	v_mfma_f32_16x16x32_f16 v[100:103], v[68:71], v[180:183], v[100:103]
	v_mfma_f32_16x16x32_f16 v[8:11], v[76:79], v[180:183], v[8:11]
	v_mfma_f32_16x16x32_f16 v[112:115], v[68:71], v[188:191], v[112:115]
	v_mfma_f32_16x16x32_f16 v[4:7], v[76:79], v[188:191], v[4:7]
	v_mfma_f32_16x16x32_f16 v[128:131], v[72:75], v[168:171], v[128:131]
	v_mfma_f32_16x16x32_f16 v[32:35], v[80:83], v[168:171], v[32:35]
	v_mfma_f32_16x16x32_f16 v[120:123], v[72:75], v[176:179], v[120:123]
	v_mfma_f32_16x16x32_f16 v[24:27], v[80:83], v[176:179], v[24:27]
	v_mfma_f32_16x16x32_f16 v[100:103], v[72:75], v[184:187], v[100:103]
	v_mfma_f32_16x16x32_f16 v[8:11], v[80:83], v[184:187], v[8:11]
	v_mfma_f32_16x16x32_f16 v[112:115], v[72:75], v[192:195], v[112:115]
	v_mfma_f32_16x16x32_f16 v[4:7], v[80:83], v[192:195], v[4:7]
	v_mfma_f32_16x16x32_f16 v[28:31], v[92:95], v[164:167], v[28:31]
	v_mfma_f32_16x16x32_f16 v[20:23], v[92:95], v[172:175], v[20:23]
	v_mfma_f32_16x16x32_f16 v[16:19], v[92:95], v[180:183], v[16:19]
	v_mfma_f32_16x16x32_f16 v[12:15], v[92:95], v[188:191], v[12:15]
	v_mfma_f32_16x16x32_f16 v[68:71], v[84:87], v[164:167], v[124:127]
	v_mfma_f32_16x16x32_f16 v[28:31], v[96:99], v[168:171], v[28:31]
	v_mfma_f32_16x16x32_f16 v[72:75], v[84:87], v[172:175], v[116:119]
	v_mfma_f32_16x16x32_f16 v[20:23], v[96:99], v[176:179], v[20:23]
	v_mfma_f32_16x16x32_f16 v[76:79], v[84:87], v[180:183], v[108:111]
	v_mfma_f32_16x16x32_f16 v[16:19], v[96:99], v[184:187], v[16:19]
	v_mfma_f32_16x16x32_f16 v[80:83], v[84:87], v[188:191], v[104:107]
	v_mfma_f32_16x16x32_f16 v[12:15], v[96:99], v[192:195], v[12:15]
	v_mfma_f32_16x16x32_f16 v[68:71], v[88:91], v[168:171], v[68:71]
	v_mfma_f32_16x16x32_f16 v[72:75], v[88:91], v[176:179], v[72:75]
	v_mfma_f32_16x16x32_f16 v[76:79], v[88:91], v[184:187], v[76:79]
	v_mfma_f32_16x16x32_f16 v[80:83], v[88:91], v[192:195], v[80:83]
	s_barrier
	s_add_i32 s45, 0, 0x18000
	s_add_i32 s63, 0, 0x1c000
	v_add_u32_e32 v96, s45, v244
	v_add_u32_e32 v104, s63, v244
	ds_read_b128 v[84:87], v96
	ds_read_b128 v[88:91], v96 offset:1024
	ds_read_b128 v[92:95], v96 offset:2048
	ds_read_b128 v[96:99], v96 offset:3072
	ds_read_b128 v[164:167], v104
	ds_read_b128 v[168:171], v104 offset:1024
	ds_read_b128 v[172:175], v104 offset:2048
	ds_read_b128 v[176:179], v104 offset:3072
	s_add_u32 s6, s40, 0x80000
	s_addc_u32 s7, s41, 0
	s_mov_b32 m0, s54
	v_lshl_add_u64 v[218:219], s[6:7], 0, v[0:1]
	ds_read_b128 v[104:107], v245 offset:32768
	ds_read_b128 v[108:111], v245 offset:33792
	ds_read_b128 v[116:119], v245 offset:34816
	ds_read_b128 v[124:127], v245 offset:35840
	ds_read_b128 v[180:183], v245 offset:36864
	ds_read_b128 v[184:187], v245 offset:37888
	ds_read_b128 v[188:191], v245 offset:38912
	ds_read_b128 v[192:195], v245 offset:39936
	global_load_lds_dwordx4 v[218:219], off
	v_lshl_add_u64 v[218:219], s[6:7], 0, v[210:211]
	s_mov_b32 m0, s55
	s_nop 0
	global_load_lds_dwordx4 v[218:219], off
	s_waitcnt vmcnt(8)
	s_waitcnt lgkmcnt(0)
	s_barrier
	s_waitcnt lgkmcnt(0)
	v_mfma_f32_16x16x32_f16 v[160:163], v[84:87], v[104:107], v[160:163]
	v_mfma_f32_16x16x32_f16 v[64:67], v[92:95], v[104:107], v[64:67]
	v_mfma_f32_16x16x32_f16 v[148:151], v[84:87], v[116:119], v[148:151]
	v_mfma_f32_16x16x32_f16 v[48:51], v[92:95], v[116:119], v[48:51]
	v_mfma_f32_16x16x32_f16 v[132:135], v[84:87], v[180:183], v[132:135]
	v_mfma_f32_16x16x32_f16 v[36:39], v[92:95], v[180:183], v[36:39]
	v_mfma_f32_16x16x32_f16 v[144:147], v[84:87], v[188:191], v[144:147]
	v_mfma_f32_16x16x32_f16 v[44:47], v[92:95], v[188:191], v[44:47]
	v_mfma_f32_16x16x32_f16 v[160:163], v[88:91], v[108:111], v[160:163]
	v_mfma_f32_16x16x32_f16 v[64:67], v[96:99], v[108:111], v[64:67]
	v_mfma_f32_16x16x32_f16 v[148:151], v[88:91], v[124:127], v[148:151]
	v_mfma_f32_16x16x32_f16 v[48:51], v[96:99], v[124:127], v[48:51]
	v_mfma_f32_16x16x32_f16 v[132:135], v[88:91], v[184:187], v[132:135]
	v_mfma_f32_16x16x32_f16 v[36:39], v[96:99], v[184:187], v[36:39]
	v_mfma_f32_16x16x32_f16 v[144:147], v[88:91], v[192:195], v[144:147]
	v_mfma_f32_16x16x32_f16 v[44:47], v[96:99], v[192:195], v[44:47]
	v_mfma_f32_16x16x32_f16 v[156:159], v[164:167], v[104:107], v[156:159]
	v_mfma_f32_16x16x32_f16 v[60:63], v[172:175], v[104:107], v[60:63]
	v_mfma_f32_16x16x32_f16 v[152:155], v[164:167], v[116:119], v[152:155]
	v_mfma_f32_16x16x32_f16 v[56:59], v[172:175], v[116:119], v[56:59]
	v_mfma_f32_16x16x32_f16 v[140:143], v[164:167], v[180:183], v[140:143]
	v_mfma_f32_16x16x32_f16 v[40:43], v[172:175], v[180:183], v[40:43]
	v_mfma_f32_16x16x32_f16 v[136:139], v[164:167], v[188:191], v[136:139]
	v_mfma_f32_16x16x32_f16 v[52:55], v[172:175], v[188:191], v[52:55]
	v_mfma_f32_16x16x32_f16 v[156:159], v[168:171], v[108:111], v[156:159]
	v_mfma_f32_16x16x32_f16 v[60:63], v[176:179], v[108:111], v[60:63]
	v_mfma_f32_16x16x32_f16 v[152:155], v[168:171], v[124:127], v[152:155]
	v_mfma_f32_16x16x32_f16 v[56:59], v[176:179], v[124:127], v[56:59]
	v_mfma_f32_16x16x32_f16 v[140:143], v[168:171], v[184:187], v[140:143]
	v_mfma_f32_16x16x32_f16 v[40:43], v[176:179], v[184:187], v[40:43]
	v_mfma_f32_16x16x32_f16 v[136:139], v[168:171], v[192:195], v[136:139]
	v_mfma_f32_16x16x32_f16 v[52:55], v[176:179], v[192:195], v[52:55]
	s_barrier
; #define PG8_STAGE(bufoff, gbase, voff) do { _Pragma("unroll") for (int _i = 0; _i < 2; ++_i) \
;         __builtin_amdgcn_global_load_lds((const unsigned*)((const char*)(gbase) + (voff)[_i]), (LAS unsigned*)(lds + (bufoff) + ldsw + _i * 8192), 16, 0, 0); } while (0)
; #define PG8_LDA(dst, b, h) do { _Pragma("unroll") for (int m = 0; m < 4; ++m) _Pragma("unroll") for (int k = 0; k < 2; ++k) dst[m][k] = *(const LAS bf16x8*)(lds + PG8_SA(b, h) + aoff + m * 2048 + k * 1024); } while (0)
; #define PG8_WAIT_V(n) asm volatile("s_waitcnt vmcnt(" #n ")" ::: "memory")
; #define PG8_WAIT_L(n) asm volatile("s_waitcnt lgkmcnt(" #n ")" ::: "memory")
; #define PG8_BAR __builtin_amdgcn_s_barrier()
; #define PG8_SCHED __builtin_amdgcn_sched_barrier(0)
; template <class Epi, class Sched, bool FUSED = false, bool APERM = false>
; __device__ __forceinline__ void gemm_phase(int wid_s, LAS unsigned char* lds, const Gemm g, const Sched& S, const Epi& E) {
;     ...
;             PG8_LDA(At, 1, 1); PG8_STAGE(PG8_SB(1, 0), b3, voffB); PG8_STAGE(PG8_SB(1, 1), b3 + hstep, voffB); PG8_STAGE(PG8_SA(1, 0), a3, voffA);
;             PG8_WAIT_V(8); PG8_WAIT_L(0); PG8_BAR; PG8_MMA(1, 0, At, B0); PG8_MMA(1, 1, At, B1); PG8_BAR; PG8_SCHED;
;         }
;         if (wr == 0) PG8_BAR;
	s_add_i32 s6, s45, s51
	v_lshl_add_u64 v[104:105], v[200:201], 0, s[12:13]
	s_mov_b32 m0, s6
	ds_read_b128 v[180:183], v245 offset:49152
	ds_read_b128 v[184:187], v245 offset:50176
	ds_read_b128 v[188:191], v245 offset:51200
	ds_read_b128 v[192:195], v245 offset:52224
	ds_read_b128 v[218:221], v245 offset:53248
	ds_read_b128 v[222:225], v245 offset:54272
	ds_read_b128 v[226:229], v245 offset:55296
	ds_read_b128 v[230:233], v245 offset:56320
	global_load_lds_dwordx4 v[104:105], off
	s_add_i32 m0, s6, 0x2000
	s_add_u32 s6, s38, 0x80080
	v_lshl_add_u64 v[104:105], v[234:235], 0, s[12:13]
	s_addc_u32 s7, s39, 0
	s_add_i32 s38, s63, s51
	global_load_lds_dwordx4 v[104:105], off
	v_lshl_add_u64 v[104:105], s[6:7], 0, v[208:209]
	s_mov_b32 m0, s38
	s_nop 0
	global_load_lds_dwordx4 v[104:105], off
	v_lshl_add_u64 v[104:105], s[6:7], 0, v[212:213]
	s_add_i32 m0, s38, 0x2000
	s_nop 0
	global_load_lds_dwordx4 v[104:105], off
	v_lshl_add_u64 v[104:105], v[236:237], 0, s[12:13]
	s_mov_b32 m0, s59
	s_nop 0
	global_load_lds_dwordx4 v[104:105], off
	v_lshl_add_u64 v[104:105], v[238:239], 0, s[12:13]
	s_mov_b32 m0, s60
	s_nop 0
	global_load_lds_dwordx4 v[104:105], off
	s_waitcnt vmcnt(8)
	s_waitcnt lgkmcnt(0)
	s_barrier
	s_waitcnt lgkmcnt(0)
	v_mfma_f32_16x16x32_f16 v[104:107], v[84:87], v[180:183], v[128:131]
	v_mfma_f32_16x16x32_f16 v[128:131], v[88:91], v[184:187], v[104:107]
	v_mfma_f32_16x16x32_f16 v[104:107], v[84:87], v[188:191], v[120:123]
	v_mfma_f32_16x16x32_f16 v[32:35], v[92:95], v[180:183], v[32:35]
	v_mfma_f32_16x16x32_f16 v[120:123], v[88:91], v[192:195], v[104:107]
	v_mfma_f32_16x16x32_f16 v[24:27], v[92:95], v[188:191], v[24:27]
	v_mfma_f32_16x16x32_f16 v[100:103], v[84:87], v[218:221], v[100:103]
	v_mfma_f32_16x16x32_f16 v[8:11], v[92:95], v[218:221], v[8:11]
	v_mfma_f32_16x16x32_f16 v[104:107], v[84:87], v[226:229], v[112:115]
	v_mfma_f32_16x16x32_f16 v[4:7], v[92:95], v[226:229], v[4:7]
	v_mfma_f32_16x16x32_f16 v[32:35], v[96:99], v[184:187], v[32:35]
	v_mfma_f32_16x16x32_f16 v[24:27], v[96:99], v[192:195], v[24:27]
	v_mfma_f32_16x16x32_f16 v[100:103], v[88:91], v[222:225], v[100:103]
	v_mfma_f32_16x16x32_f16 v[8:11], v[96:99], v[222:225], v[8:11]
	v_mfma_f32_16x16x32_f16 v[112:115], v[88:91], v[230:233], v[104:107]
	v_mfma_f32_16x16x32_f16 v[4:7], v[96:99], v[230:233], v[4:7]
	v_mfma_f32_16x16x32_f16 v[68:71], v[164:167], v[180:183], v[68:71]
	v_mfma_f32_16x16x32_f16 v[124:127], v[168:171], v[184:187], v[68:71]
	v_mfma_f32_16x16x32_f16 v[68:71], v[164:167], v[188:191], v[72:75]
	v_mfma_f32_16x16x32_f16 v[116:119], v[168:171], v[192:195], v[68:71]
	v_mfma_f32_16x16x32_f16 v[68:71], v[164:167], v[218:221], v[76:79]
	v_mfma_f32_16x16x32_f16 v[28:31], v[172:175], v[180:183], v[28:31]
	v_mfma_f32_16x16x32_f16 v[20:23], v[172:175], v[188:191], v[20:23]
	v_mfma_f32_16x16x32_f16 v[108:111], v[168:171], v[222:225], v[68:71]
	v_mfma_f32_16x16x32_f16 v[16:19], v[172:175], v[218:221], v[16:19]
	v_mfma_f32_16x16x32_f16 v[68:71], v[164:167], v[226:229], v[80:83]
	v_mfma_f32_16x16x32_f16 v[12:15], v[172:175], v[226:229], v[12:15]
	v_mfma_f32_16x16x32_f16 v[28:31], v[176:179], v[184:187], v[28:31]
	v_mfma_f32_16x16x32_f16 v[20:23], v[176:179], v[192:195], v[20:23]
	v_mfma_f32_16x16x32_f16 v[16:19], v[176:179], v[222:225], v[16:19]
	v_mfma_f32_16x16x32_f16 v[104:107], v[168:171], v[230:233], v[68:71]
	v_mfma_f32_16x16x32_f16 v[12:15], v[176:179], v[230:233], v[12:15]
	s_barrier
	s_add_i32 s44, s44, 2
	s_add_u32 s42, s42, 0x100
	s_addc_u32 s43, s43, 0
	s_cmp_gt_u32 s44, 29
	s_mov_b64 s[6:7], s[36:37]
	s_cbranch_scc0 .LBB0_754
	s_and_b64 vcc, exec, s[24:25]
	s_cbranch_vccz .LBB0_757
	s_barrier

; #define PG8_STAGE(bufoff, gbase, voff) do { _Pragma("unroll") for (int _i = 0; _i < 2; ++_i) \
;         __builtin_amdgcn_global_load_lds((const unsigned*)((const char*)(gbase) + (voff)[_i]), (LAS unsigned*)(lds + (bufoff) + ldsw + _i * 8192), 16, 0, 0); } while (0)
; #define PG8_LDA(dst, b, h) do { _Pragma("unroll") for (int m = 0; m < 4; ++m) _Pragma("unroll") for (int k = 0; k < 2; ++k) dst[m][k] = *(const LAS bf16x8*)(lds + PG8_SA(b, h) + aoff + m * 2048 + k * 1024); } while (0)
; #define PG8_LDB(dst, b, h) do { _Pragma("unroll") for (int n = 0; n < 2; ++n) _Pragma("unroll") for (int k = 0; k < 2; ++k) dst[n][k] = *(const LAS bf16x8*)(lds + PG8_SB(b, h) + boff + n * 2048 + k * 1024); } while (0)
; #define PG8_WAIT_V(n) asm volatile("s_waitcnt vmcnt(" #n ")" ::: "memory")
; #define PG8_WAIT_L(n) asm volatile("s_waitcnt lgkmcnt(" #n ")" ::: "memory")
; #define PG8_BAR __builtin_amdgcn_s_barrier()
; #define PG8_SCHED __builtin_amdgcn_sched_barrier(0)
; template <class Epi, class Sched, bool FUSED = false, bool APERM = false>
; __device__ __forceinline__ void gemm_phase(int wid_s, LAS unsigned char* lds, const Gemm g, const Sched& S, const Epi& E) {
;     ...
;             const bool last = (t == nt - 2);
;             const char* a1 = cA + (size_t)(t + 1) * kstep;
;             const char* a2 = last ? nA : cA + (size_t)(t + 2) * kstep; const char* b2 = last ? nB : cB + (size_t)(t + 2) * kstep;
;             const char* a3 = a2 + kstep; const char* b3 = b2 + kstep;
;             if (last && has_next) S.a_ready(nxt);
;             PG8_LDB(B0, 0, 0); PG8_LDB(B1, 0, 1); PG8_SCHED; PG8_LDA(At, 0, 0); PG8_STAGE(PG8_SA(1, 1), a1 + hstep, voffA);
;             PG8_WAIT_V(8); PG8_WAIT_L(0); PG8_BAR; PG8_MMA(0, 0, At, B0); PG8_MMA(0, 1, At, B1); PG8_BAR; PG8_SCHED;
;             PG8_LDA(At, 0, 1); PG8_STAGE(PG8_SB(0, 0), b2, voffB); PG8_STAGE(PG8_SB(0, 1), b2 + hstep, voffB); PG8_STAGE(PG8_SA(0, 0), a2, voffA);
.LBB0_929:
	s_add_u32 s36, s28, s34
	s_addc_u32 s37, s29, s35
	s_add_u32 s36, s36, 0x100
	s_addc_u32 s37, s37, 0
	s_add_u32 s63, s60, s34
	s_addc_u32 s64, s61, s35
	s_add_i32 s65, 0, 0x10000
	s_cmpk_eq_i32 s34, 0x2a00
	s_cselect_b32 s39, s5, s37
	s_cselect_b32 s38, s4, s36
	v_add_u32_e32 v143, s65, v3
	s_cselect_b32 s37, s31, s64
	s_cselect_b32 s36, s30, s63
	s_add_i32 s63, 0, 0x14000
	ds_read_b128 v[144:147], v143
	ds_read_b128 v[148:151], v143 offset:1024
	ds_read_b128 v[152:155], v143 offset:2048
	ds_read_b128 v[156:159], v143 offset:3072
	v_add_u32_e32 v143, s63, v3
	ds_read_b128 v[160:163], v143
	ds_read_b128 v[164:167], v143 offset:1024
	ds_read_b128 v[168:171], v143 offset:2048
	ds_read_b128 v[172:175], v143 offset:3072
	v_lshl_add_u64 v[200:201], v[140:141], 0, s[34:35]
	s_add_i32 m0, s49, 0xc000
	ds_read_b128 v[176:179], v142
	ds_read_b128 v[180:183], v142 offset:1024
	ds_read_b128 v[184:187], v142 offset:2048
	ds_read_b128 v[188:191], v142 offset:3072
	ds_read_b128 v[192:195], v142 offset:4096
	ds_read_b128 v[208:211], v142 offset:5120
	ds_read_b128 v[212:215], v142 offset:6144
	ds_read_b128 v[216:219], v142 offset:7168
	global_load_lds_dwordx4 v[200:201], off
	v_lshl_add_u64 v[200:201], v[138:139], 0, s[34:35]
	s_add_i32 m0, s49, 0xe000
	s_nop 0
	global_load_lds_dwordx4 v[200:201], off
	s_waitcnt vmcnt(8)
	s_waitcnt lgkmcnt(0)
	s_barrier
	s_waitcnt lgkmcnt(0)
	v_mfma_f32_16x16x32_f16 v[128:131], v[144:147], v[176:179], v[128:131]
	v_mfma_f32_16x16x32_f16 v[124:127], v[152:155], v[176:179], v[124:127]
	v_mfma_f32_16x16x32_f16 v[112:115], v[144:147], v[184:187], v[112:115]
	v_mfma_f32_16x16x32_f16 v[108:111], v[152:155], v[184:187], v[108:111]
	v_mfma_f32_16x16x32_f16 v[96:99], v[144:147], v[192:195], v[96:99]
	v_mfma_f32_16x16x32_f16 v[92:95], v[152:155], v[192:195], v[92:95]
	v_mfma_f32_16x16x32_f16 v[80:83], v[144:147], v[212:215], v[80:83]
	v_mfma_f32_16x16x32_f16 v[76:79], v[152:155], v[212:215], v[76:79]
	v_mfma_f32_16x16x32_f16 v[128:131], v[148:151], v[180:183], v[128:131]
	v_mfma_f32_16x16x32_f16 v[124:127], v[156:159], v[180:183], v[124:127]
	v_mfma_f32_16x16x32_f16 v[112:115], v[148:151], v[188:191], v[112:115]
	v_mfma_f32_16x16x32_f16 v[108:111], v[156:159], v[188:191], v[108:111]
	v_mfma_f32_16x16x32_f16 v[96:99], v[148:151], v[208:211], v[96:99]
	v_mfma_f32_16x16x32_f16 v[92:95], v[156:159], v[208:211], v[92:95]
	v_mfma_f32_16x16x32_f16 v[80:83], v[148:151], v[216:219], v[80:83]
	v_mfma_f32_16x16x32_f16 v[76:79], v[156:159], v[216:219], v[76:79]
	v_mfma_f32_16x16x32_f16 v[120:123], v[160:163], v[176:179], v[120:123]
	v_mfma_f32_16x16x32_f16 v[116:119], v[168:171], v[176:179], v[116:119]
	v_mfma_f32_16x16x32_f16 v[104:107], v[160:163], v[184:187], v[104:107]
	v_mfma_f32_16x16x32_f16 v[100:103], v[168:171], v[184:187], v[100:103]
	v_mfma_f32_16x16x32_f16 v[88:91], v[160:163], v[192:195], v[88:91]
	v_mfma_f32_16x16x32_f16 v[84:87], v[168:171], v[192:195], v[84:87]
	v_mfma_f32_16x16x32_f16 v[72:75], v[160:163], v[212:215], v[72:75]
	v_mfma_f32_16x16x32_f16 v[68:71], v[168:171], v[212:215], v[68:71]
	v_mfma_f32_16x16x32_f16 v[120:123], v[164:167], v[180:183], v[120:123]
	v_mfma_f32_16x16x32_f16 v[116:119], v[172:175], v[180:183], v[116:119]
	v_mfma_f32_16x16x32_f16 v[104:107], v[164:167], v[188:191], v[104:107]
	v_mfma_f32_16x16x32_f16 v[100:103], v[172:175], v[188:191], v[100:103]
	v_mfma_f32_16x16x32_f16 v[88:91], v[164:167], v[208:211], v[88:91]
	v_mfma_f32_16x16x32_f16 v[84:87], v[172:175], v[208:211], v[84:87]
	v_mfma_f32_16x16x32_f16 v[72:75], v[164:167], v[216:219], v[72:75]
	v_mfma_f32_16x16x32_f16 v[68:71], v[172:175], v[216:219], v[68:71]
	s_barrier
	s_add_i32 s64, s65, s48
	v_lshl_add_u64 v[200:201], s[36:37], 0, v[0:1]
	s_mov_b32 m0, s64
	ds_read_b128 v[176:179], v142 offset:16384
	ds_read_b128 v[180:183], v142 offset:17408
	ds_read_b128 v[184:187], v142 offset:18432
	ds_read_b128 v[188:191], v142 offset:19456
	ds_read_b128 v[192:195], v142 offset:20480
	ds_read_b128 v[208:211], v142 offset:21504
	ds_read_b128 v[212:215], v142 offset:22528
	ds_read_b128 v[216:219], v142 offset:23552
	global_load_lds_dwordx4 v[200:201], off
	s_add_i32 m0, s64, 0x2000
	s_add_u32 s64, s36, 0x158000
	v_lshl_add_u64 v[222:223], s[36:37], 0, v[132:133]
	s_addc_u32 s65, s37, 0
	s_add_i32 s63, s63, s48
	global_load_lds_dwordx4 v[222:223], off
	v_lshl_add_u64 v[224:225], s[64:65], 0, v[0:1]
	s_mov_b32 m0, s63
	v_lshl_add_u64 v[226:227], s[38:39], 0, v[132:133]
	global_load_lds_dwordx4 v[224:225], off
	v_lshl_add_u64 v[224:225], s[64:65], 0, v[132:133]
	s_add_i32 m0, s63, 0x2000
	s_nop 0
	global_load_lds_dwordx4 v[224:225], off
	v_lshl_add_u64 v[224:225], s[38:39], 0, v[0:1]
	s_mov_b32 m0, s49
	s_nop 0
	global_load_lds_dwordx4 v[224:225], off
	s_mov_b32 m0, s50
	s_nop 0
	global_load_lds_dwordx4 v[226:227], off
	s_waitcnt vmcnt(8)
	s_waitcnt lgkmcnt(0)
	s_barrier
; #define PG8_STAGE(bufoff, gbase, voff) do { _Pragma("unroll") for (int _i = 0; _i < 2; ++_i) \
;         __builtin_amdgcn_global_load_lds((const unsigned*)((const char*)(gbase) + (voff)[_i]), (LAS unsigned*)(lds + (bufoff) + ldsw + _i * 8192), 16, 0, 0); } while (0)
; #define PG8_LDA(dst, b, h) do { _Pragma("unroll") for (int m = 0; m < 4; ++m) _Pragma("unroll") for (int k = 0; k < 2; ++k) dst[m][k] = *(const LAS bf16x8*)(lds + PG8_SA(b, h) + aoff + m * 2048 + k * 1024); } while (0)
; #define PG8_LDB(dst, b, h) do { _Pragma("unroll") for (int n = 0; n < 2; ++n) _Pragma("unroll") for (int k = 0; k < 2; ++k) dst[n][k] = *(const LAS bf16x8*)(lds + PG8_SB(b, h) + boff + n * 2048 + k * 1024); } while (0)
; #define PG8_WAIT_V(n) asm volatile("s_waitcnt vmcnt(" #n ")" ::: "memory")
; #define PG8_WAIT_L(n) asm volatile("s_waitcnt lgkmcnt(" #n ")" ::: "memory")
; #define PG8_BAR __builtin_amdgcn_s_barrier()
; #define PG8_SCHED __builtin_amdgcn_sched_barrier(0)
; template <class Epi, class Sched, bool FUSED = false, bool APERM = false>
; __device__ __forceinline__ void gemm_phase(int wid_s, LAS unsigned char* lds, const Gemm g, const Sched& S, const Epi& E) {
;     ...
;             PG8_WAIT_V(8); PG8_WAIT_L(0); PG8_BAR; PG8_MMA(1, 0, At, B0); PG8_MMA(1, 1, At, B1); PG8_BAR; PG8_SCHED;
;             PG8_LDB(B0, 1, 0); PG8_LDB(B1, 1, 1); PG8_SCHED; PG8_LDA(At, 1, 0); PG8_STAGE(PG8_SA(0, 1), a2 + hstep, voffA);
;             PG8_WAIT_V(8); PG8_WAIT_L(0); PG8_BAR; PG8_MMA(0, 0, At, B0); PG8_MMA(0, 1, At, B1); PG8_BAR; PG8_SCHED;
	s_waitcnt lgkmcnt(0)
	v_mfma_f32_16x16x32_f16 v[64:67], v[144:147], v[176:179], v[64:67]
	v_mfma_f32_16x16x32_f16 v[60:63], v[152:155], v[176:179], v[60:63]
	v_mfma_f32_16x16x32_f16 v[48:51], v[144:147], v[184:187], v[48:51]
	v_mfma_f32_16x16x32_f16 v[44:47], v[152:155], v[184:187], v[44:47]
	v_mfma_f32_16x16x32_f16 v[32:35], v[144:147], v[192:195], v[32:35]
	v_mfma_f32_16x16x32_f16 v[28:31], v[152:155], v[192:195], v[28:31]
	v_mfma_f32_16x16x32_f16 v[16:19], v[144:147], v[212:215], v[16:19]
	v_mfma_f32_16x16x32_f16 v[12:15], v[152:155], v[212:215], v[12:15]
	v_mfma_f32_16x16x32_f16 v[64:67], v[148:151], v[180:183], v[64:67]
	v_mfma_f32_16x16x32_f16 v[60:63], v[156:159], v[180:183], v[60:63]
	v_mfma_f32_16x16x32_f16 v[48:51], v[148:151], v[188:191], v[48:51]
	v_mfma_f32_16x16x32_f16 v[44:47], v[156:159], v[188:191], v[44:47]
	v_mfma_f32_16x16x32_f16 v[32:35], v[148:151], v[208:211], v[32:35]
	v_mfma_f32_16x16x32_f16 v[28:31], v[156:159], v[208:211], v[28:31]
	v_mfma_f32_16x16x32_f16 v[16:19], v[148:151], v[216:219], v[16:19]
	v_mfma_f32_16x16x32_f16 v[12:15], v[156:159], v[216:219], v[12:15]
	v_mfma_f32_16x16x32_f16 v[56:59], v[160:163], v[176:179], v[56:59]
	v_mfma_f32_16x16x32_f16 v[52:55], v[168:171], v[176:179], v[52:55]
	v_mfma_f32_16x16x32_f16 v[40:43], v[160:163], v[184:187], v[40:43]
	v_mfma_f32_16x16x32_f16 v[36:39], v[168:171], v[184:187], v[36:39]
	v_mfma_f32_16x16x32_f16 v[24:27], v[160:163], v[192:195], v[24:27]
	v_mfma_f32_16x16x32_f16 v[20:23], v[168:171], v[192:195], v[20:23]
	v_mfma_f32_16x16x32_f16 v[8:11], v[160:163], v[212:215], v[8:11]
	v_mfma_f32_16x16x32_f16 v[4:7], v[168:171], v[212:215], v[4:7]
	v_mfma_f32_16x16x32_f16 v[56:59], v[164:167], v[180:183], v[56:59]
	v_mfma_f32_16x16x32_f16 v[52:55], v[172:175], v[180:183], v[52:55]
	v_mfma_f32_16x16x32_f16 v[40:43], v[164:167], v[188:191], v[40:43]
	v_mfma_f32_16x16x32_f16 v[36:39], v[172:175], v[188:191], v[36:39]
	v_mfma_f32_16x16x32_f16 v[24:27], v[164:167], v[208:211], v[24:27]
	v_mfma_f32_16x16x32_f16 v[20:23], v[172:175], v[208:211], v[20:23]
	v_mfma_f32_16x16x32_f16 v[8:11], v[164:167], v[216:219], v[8:11]
	v_mfma_f32_16x16x32_f16 v[4:7], v[172:175], v[216:219], v[4:7]
	s_barrier
	s_add_i32 s63, 0, 0x18000
	v_add_u32_e32 v143, s63, v3
	s_add_i32 s64, 0, 0x1c000
	ds_read_b128 v[144:147], v143
	ds_read_b128 v[148:151], v143 offset:1024
	ds_read_b128 v[152:155], v143 offset:2048
	ds_read_b128 v[156:159], v143 offset:3072
	v_add_u32_e32 v143, s64, v3
	ds_read_b128 v[160:163], v143
	ds_read_b128 v[164:167], v143 offset:1024
	ds_read_b128 v[168:171], v143 offset:2048
	ds_read_b128 v[172:175], v143 offset:3072
	s_add_u32 s38, s38, 0x158000
	s_addc_u32 s39, s39, 0
	s_mov_b32 m0, s51
	v_lshl_add_u64 v[228:229], s[38:39], 0, v[0:1]
	ds_read_b128 v[176:179], v142 offset:32768
	ds_read_b128 v[180:183], v142 offset:33792
	ds_read_b128 v[184:187], v142 offset:34816
	ds_read_b128 v[188:191], v142 offset:35840
	ds_read_b128 v[192:195], v142 offset:36864
	ds_read_b128 v[208:211], v142 offset:37888
	ds_read_b128 v[212:215], v142 offset:38912
	ds_read_b128 v[216:219], v142 offset:39936
	global_load_lds_dwordx4 v[228:229], off
	v_lshl_add_u64 v[228:229], s[38:39], 0, v[132:133]
	s_mov_b32 m0, s52
	s_nop 0
	global_load_lds_dwordx4 v[228:229], off
	s_waitcnt vmcnt(8)
	s_waitcnt lgkmcnt(0)
	s_barrier
	s_waitcnt lgkmcnt(0)
	v_mfma_f32_16x16x32_f16 v[128:131], v[144:147], v[176:179], v[128:131]
	v_mfma_f32_16x16x32_f16 v[124:127], v[152:155], v[176:179], v[124:127]
	v_mfma_f32_16x16x32_f16 v[112:115], v[144:147], v[184:187], v[112:115]
	v_mfma_f32_16x16x32_f16 v[108:111], v[152:155], v[184:187], v[108:111]
	v_mfma_f32_16x16x32_f16 v[96:99], v[144:147], v[192:195], v[96:99]
	v_mfma_f32_16x16x32_f16 v[92:95], v[152:155], v[192:195], v[92:95]
	v_mfma_f32_16x16x32_f16 v[80:83], v[144:147], v[212:215], v[80:83]
	v_mfma_f32_16x16x32_f16 v[76:79], v[152:155], v[212:215], v[76:79]
	v_mfma_f32_16x16x32_f16 v[128:131], v[148:151], v[180:183], v[128:131]
	v_mfma_f32_16x16x32_f16 v[124:127], v[156:159], v[180:183], v[124:127]
	v_mfma_f32_16x16x32_f16 v[112:115], v[148:151], v[188:191], v[112:115]
	v_mfma_f32_16x16x32_f16 v[108:111], v[156:159], v[188:191], v[108:111]
	v_mfma_f32_16x16x32_f16 v[96:99], v[148:151], v[208:211], v[96:99]
	v_mfma_f32_16x16x32_f16 v[92:95], v[156:159], v[208:211], v[92:95]
	v_mfma_f32_16x16x32_f16 v[80:83], v[148:151], v[216:219], v[80:83]
	v_mfma_f32_16x16x32_f16 v[76:79], v[156:159], v[216:219], v[76:79]
	v_mfma_f32_16x16x32_f16 v[120:123], v[160:163], v[176:179], v[120:123]
	v_mfma_f32_16x16x32_f16 v[116:119], v[168:171], v[176:179], v[116:119]
	v_mfma_f32_16x16x32_f16 v[104:107], v[160:163], v[184:187], v[104:107]
	v_mfma_f32_16x16x32_f16 v[100:103], v[168:171], v[184:187], v[100:103]
	v_mfma_f32_16x16x32_f16 v[88:91], v[160:163], v[192:195], v[88:91]
	v_mfma_f32_16x16x32_f16 v[84:87], v[168:171], v[192:195], v[84:87]
	v_mfma_f32_16x16x32_f16 v[72:75], v[160:163], v[212:215], v[72:75]
	v_mfma_f32_16x16x32_f16 v[68:71], v[168:171], v[212:215], v[68:71]
	v_mfma_f32_16x16x32_f16 v[120:123], v[164:167], v[180:183], v[120:123]
	v_mfma_f32_16x16x32_f16 v[116:119], v[172:175], v[180:183], v[116:119]
	v_mfma_f32_16x16x32_f16 v[104:107], v[164:167], v[188:191], v[104:107]
	v_mfma_f32_16x16x32_f16 v[100:103], v[172:175], v[188:191], v[100:103]
	v_mfma_f32_16x16x32_f16 v[88:91], v[164:167], v[208:211], v[88:91]
	v_mfma_f32_16x16x32_f16 v[84:87], v[172:175], v[208:211], v[84:87]
	v_mfma_f32_16x16x32_f16 v[72:75], v[164:167], v[216:219], v[72:75]
	v_mfma_f32_16x16x32_f16 v[68:71], v[172:175], v[216:219], v[68:71]
	s_barrier
; #define PG8_STAGE(bufoff, gbase, voff) do { _Pragma("unroll") for (int _i = 0; _i < 2; ++_i) \
;         __builtin_amdgcn_global_load_lds((const unsigned*)((const char*)(gbase) + (voff)[_i]), (LAS unsigned*)(lds + (bufoff) + ldsw + _i * 8192), 16, 0, 0); } while (0)
; #define PG8_LDA(dst, b, h) do { _Pragma("unroll") for (int m = 0; m < 4; ++m) _Pragma("unroll") for (int k = 0; k < 2; ++k) dst[m][k] = *(const LAS bf16x8*)(lds + PG8_SA(b, h) + aoff + m * 2048 + k * 1024); } while (0)
; #define PG8_WAIT_V(n) asm volatile("s_waitcnt vmcnt(" #n ")" ::: "memory")
; #define PG8_WAIT_L(n) asm volatile("s_waitcnt lgkmcnt(" #n ")" ::: "memory")
; #define PG8_BAR __builtin_amdgcn_s_barrier()
; #define PG8_SCHED __builtin_amdgcn_sched_barrier(0)
; template <class Epi, class Sched, bool FUSED = false, bool APERM = false>
; __device__ __forceinline__ void gemm_phase(int wid_s, LAS unsigned char* lds, const Gemm g, const Sched& S, const Epi& E) {
;     ...
;             PG8_LDA(At, 1, 1); PG8_STAGE(PG8_SB(1, 0), b3, voffB); PG8_STAGE(PG8_SB(1, 1), b3 + hstep, voffB); PG8_STAGE(PG8_SA(1, 0), a3, voffA);
;             PG8_WAIT_V(8); PG8_WAIT_L(0); PG8_BAR; PG8_MMA(1, 0, At, B0); PG8_MMA(1, 1, At, B1); PG8_BAR; PG8_SCHED;
;         }
;         if (wr == 0) PG8_BAR;
	s_add_i32 s38, s63, s48
	v_lshl_add_u64 v[200:201], v[200:201], 0, s[12:13]
	s_mov_b32 m0, s38
	ds_read_b128 v[176:179], v142 offset:49152
	ds_read_b128 v[180:183], v142 offset:50176
	ds_read_b128 v[184:187], v142 offset:51200
	ds_read_b128 v[188:191], v142 offset:52224
	ds_read_b128 v[192:195], v142 offset:53248
	ds_read_b128 v[208:211], v142 offset:54272
	ds_read_b128 v[212:215], v142 offset:55296
	ds_read_b128 v[216:219], v142 offset:56320
	global_load_lds_dwordx4 v[200:201], off
	s_add_i32 m0, s38, 0x2000
	s_add_u32 s36, s36, 0x158080
	v_lshl_add_u64 v[200:201], v[222:223], 0, s[12:13]
	s_addc_u32 s37, s37, 0
	s_add_i32 s38, s64, s48
	global_load_lds_dwordx4 v[200:201], off
	v_lshl_add_u64 v[200:201], s[36:37], 0, v[0:1]
	s_mov_b32 m0, s38
	s_nop 0
	global_load_lds_dwordx4 v[200:201], off
	v_lshl_add_u64 v[200:201], s[36:37], 0, v[132:133]
	s_add_i32 m0, s38, 0x2000
	s_nop 0
	global_load_lds_dwordx4 v[200:201], off
	v_lshl_add_u64 v[200:201], v[224:225], 0, s[12:13]
	s_mov_b32 m0, s54
	s_nop 0
	global_load_lds_dwordx4 v[200:201], off
	v_lshl_add_u64 v[200:201], v[226:227], 0, s[12:13]
	s_mov_b32 m0, s55
	s_nop 0
	global_load_lds_dwordx4 v[200:201], off
	s_waitcnt vmcnt(8)
	s_waitcnt lgkmcnt(0)
	s_barrier
	s_waitcnt lgkmcnt(0)
	v_mfma_f32_16x16x32_f16 v[64:67], v[144:147], v[176:179], v[64:67]
	v_mfma_f32_16x16x32_f16 v[60:63], v[152:155], v[176:179], v[60:63]
	v_mfma_f32_16x16x32_f16 v[48:51], v[144:147], v[184:187], v[48:51]
	v_mfma_f32_16x16x32_f16 v[44:47], v[152:155], v[184:187], v[44:47]
	v_mfma_f32_16x16x32_f16 v[32:35], v[144:147], v[192:195], v[32:35]
	v_mfma_f32_16x16x32_f16 v[28:31], v[152:155], v[192:195], v[28:31]
	v_mfma_f32_16x16x32_f16 v[16:19], v[144:147], v[212:215], v[16:19]
	v_mfma_f32_16x16x32_f16 v[12:15], v[152:155], v[212:215], v[12:15]
	v_mfma_f32_16x16x32_f16 v[64:67], v[148:151], v[180:183], v[64:67]
	v_mfma_f32_16x16x32_f16 v[60:63], v[156:159], v[180:183], v[60:63]
	v_mfma_f32_16x16x32_f16 v[48:51], v[148:151], v[188:191], v[48:51]
	v_mfma_f32_16x16x32_f16 v[44:47], v[156:159], v[188:191], v[44:47]
	v_mfma_f32_16x16x32_f16 v[32:35], v[148:151], v[208:211], v[32:35]
	v_mfma_f32_16x16x32_f16 v[28:31], v[156:159], v[208:211], v[28:31]
	v_mfma_f32_16x16x32_f16 v[16:19], v[148:151], v[216:219], v[16:19]
	v_mfma_f32_16x16x32_f16 v[12:15], v[156:159], v[216:219], v[12:15]
	v_mfma_f32_16x16x32_f16 v[56:59], v[160:163], v[176:179], v[56:59]
	v_mfma_f32_16x16x32_f16 v[52:55], v[168:171], v[176:179], v[52:55]
	v_mfma_f32_16x16x32_f16 v[40:43], v[160:163], v[184:187], v[40:43]
	v_mfma_f32_16x16x32_f16 v[36:39], v[168:171], v[184:187], v[36:39]
	v_mfma_f32_16x16x32_f16 v[24:27], v[160:163], v[192:195], v[24:27]
	v_mfma_f32_16x16x32_f16 v[20:23], v[168:171], v[192:195], v[20:23]
	v_mfma_f32_16x16x32_f16 v[8:11], v[160:163], v[212:215], v[8:11]
	v_mfma_f32_16x16x32_f16 v[4:7], v[168:171], v[212:215], v[4:7]
	v_mfma_f32_16x16x32_f16 v[56:59], v[164:167], v[180:183], v[56:59]
	v_mfma_f32_16x16x32_f16 v[52:55], v[172:175], v[180:183], v[52:55]
	v_mfma_f32_16x16x32_f16 v[40:43], v[164:167], v[188:191], v[40:43]
	v_mfma_f32_16x16x32_f16 v[36:39], v[172:175], v[188:191], v[36:39]
	v_mfma_f32_16x16x32_f16 v[24:27], v[164:167], v[208:211], v[24:27]
	v_mfma_f32_16x16x32_f16 v[20:23], v[172:175], v[208:211], v[20:23]
	v_mfma_f32_16x16x32_f16 v[8:11], v[164:167], v[216:219], v[8:11]
	v_mfma_f32_16x16x32_f16 v[4:7], v[172:175], v[216:219], v[4:7]
	s_barrier
	s_add_i32 s62, s62, 2
	s_add_u32 s34, s34, 0x100
	s_addc_u32 s35, s35, 0
	s_cmpk_gt_u32 s62, 0x53
	s_cbranch_scc0 .LBB0_929
	s_and_b64 vcc, exec, s[26:27]
	s_cbranch_vccz .LBB0_932
	s_barrier
